# HGRN2 chunk scan rewritten: one wave owns both value halves of an item, sample streams run concurrently on a 5th wave
# speedup vs baseline: 1.0581x; 1.0264x over previous
; __device__ __forceinline__ int tidx() { int t = threadIdx.x; asm volatile("" : "+v"(t)); return t; }
; #define INP(p, i) ldp((p).tbl, i)
; __device__ void phase_hgrn_scan(const Ctx& p, int l, LAS unsigned char* lds) {
;     unsigned char* ws = uptr(p.ws);
;     const bf16_t* PH = (const bf16_t*)(ws + OFF_A); bf16_t* OH0 = (bf16_t*)(ws + OFF_B + 2 * SLOT); bf16_t* OH1 = (bf16_t*)(ws + OFF_B + 5 * SLOT);
;     float* UCH = (float*)(ws + OFF_B + 3 * SLOT); float* PGH = (float*)(ws + OFF_SM + SM_PGH); float* PGC = (float*)(ws + OFF_PGC);
;     const int tid = tidx(); const int wave = __builtin_amdgcn_readfirstlane(tid >> 6), lane = tid & 63;
;     LAS float* L = (LAS float*)(lds + wave * 1024);
;     for (int item = bidx() * 8 + wave; item < 2048; item += gridDim.x * 8) {
;         const int kh = item & 1, half = (item >> 1) & 1, h = (item >> 2) & 3, c = (item >> 4) & 63, b = item >> 10, idx = item >> 2;
;         f2 S[32];
; #pragma unroll
;         for (int k = 0; k < 32; ++k) S[k] = (f2){0.f, 0.f};
;         float cp = 1.f;
;         hgrn_scan(PH, b * 8192 + c * 128, 128, h, half, kh, lane, lb_of(p, l, h * 128 + kh * 64 + lane), S, cp, kh ? OH1 : OH0, half == 0 ? PGC + (size_t)idx * 384 + kh * 64 : nullptr, L);
;         float* up = UCH + (size_t)idx * 16384 + (size_t)(kh * 64) * 128 + half * 64 + lane;
; #pragma unroll
;         for (int k = 0; k < 32; ++k) { up[(2 * k) * 128] = S[k][0]; up[(2 * k + 1) * 128] = S[k][1]; }
;         if (half == 0) PGH[idx * 128 + kh * 64 + lane] = cp;
;     }
;     if (wave < 2) {
;         for (int item = bidx() * 2 + wave; item < 512; item += gridDim.x * 2) {
;             const int kh = item & 1, half = (item >> 1) & 1, h = (item >> 2) & 3, s = item >> 4;
;             const size_t so = (((size_t)l * 32 + s) * 4 + h) * 16384 + (size_t)(kh * 64) * 128 + half * 64 + lane;
;             f2 S[32];
;             const float* stp = INP(p, 4) + so;
; #pragma unroll
;             for (int k = 0; k < 32; ++k) S[k] = (f2){stp[(2 * k) * 128], stp[(2 * k + 1) * 128]};
;             float cp = 1.f;
;             hgrn_scan(PH, T_P + s * 32, 32, h, half, kh, lane, lb_of(p, l, h * 128 + kh * 64 + lane), S, cp, kh ? OH1 : OH0, nullptr, L);
; #pragma unroll
;             for (int k = 0; k < 32; ++k) { p.out[O_HGS + so + (2 * k) * 128] = S[k][0]; p.out[O_HGS + so + (2 * k + 1) * 128] = S[k][1]; }
;         }
;     }
; }
.LBB0_462:
	s_andn2_b64 vcc, exec, s[0:1]
	s_cbranch_vccnz .LBB0_486
	v_readfirstlane_b32 s38, v184
	s_lshr_b32 s38, s38, 6
	s_add_u32 s24, s86, 0x5500000
	s_addc_u32 s25, s87, 0
	s_cmp_gt_u32 s38, 4
	s_cbranch_scc1 .LBB0_486
	s_cmp_eq_u32 s38, 4
	s_cbranch_scc1 .Lhs_role_s
	s_lshl_b32 s0, s90, 2
	s_add_i32 s0, s0, s38
	s_cmpk_gt_u32 s0, 0x3ff
	s_cbranch_scc1 .LBB0_486
	s_and_b32 s1, s0, 1
	s_bfe_u32 s2, s0, 0x20001
	s_lshr_b32 s3, s0, 1
	s_lshr_b32 s4, s0, 3
	s_lshl_b32 s4, s4, 7
	s_mov_b32 s36, 32
	s_lshl_b32 s5, s3, 16
	s_lshl_b32 s6, s1, 15
	s_add_i32 s5, s5, s6
	s_add_u32 s40, s86, 0xcc00000
	s_addc_u32 s41, s87, 0
	s_add_u32 s40, s40, s5
	s_addc_u32 s41, s41, 0
	s_mul_i32 s5, s3, 0x600
	s_lshl_b32 s6, s1, 8
	s_add_i32 s5, s5, s6
	s_add_u32 s42, s86, 0xec00000
	s_addc_u32 s43, s87, 0
	s_add_u32 s42, s42, s5
	s_addc_u32 s43, s43, 0
	s_lshl_b32 s5, s3, 9
	s_add_i32 s5, s5, s6
	s_add_u32 s44, s86, 0x2150000
	s_addc_u32 s45, s87, 0
	s_add_u32 s44, s44, s5
	s_addc_u32 s45, s45, 0
	s_branch .Lhs_common
.Lhs_role_s:
	s_mov_b32 s0, s90
	s_cmpk_gt_u32 s0, 0xff
	s_cbranch_scc1 .LBB0_486
	s_and_b32 s1, s0, 1
	s_bfe_u32 s2, s0, 0x20001
	s_lshr_b32 s3, s0, 3
	s_lshl_b32 s4, s3, 5
	s_add_i32 s4, s4, 0x4000
	s_mov_b32 s36, 8
	s_and_b64 s[6:7], s[34:35], exec
	s_cselect_b32 s5, 32, 0
	s_add_i32 s5, s5, s3
	s_lshl_b32 s5, s5, 2
	s_add_i32 s5, s5, s2
	s_lshr_b32 s7, s5, 16
	s_lshl_b32 s6, s5, 16
	s_lshl_b32 s5, s1, 15
	s_add_u32 s6, s6, s5
	s_addc_u32 s7, s7, 0
	s_add_u32 s40, s84, 0x4df9200
	s_addc_u32 s41, s85, 0
	s_add_u32 s40, s40, s6
	s_addc_u32 s41, s41, s7
	v_mov_b64_e32 v[0:1], s[92:93]
	flat_load_dwordx2 v[0:1], v[0:1] offset:32 sc0 sc1
	s_waitcnt vmcnt(0) lgkmcnt(0)
	v_readfirstlane_b32 s30, v0
	v_readfirstlane_b32 s31, v1
	s_add_u32 s30, s30, s6
	s_addc_u32 s31, s31, s7
.Lhs_common:
	v_and_b32_e32 v146, 63, v184
	s_mov_b32 s5, 0xee00000
	s_cmp_eq_u32 s1, 0
	s_cselect_b32 s5, 0xbb00000, s5
	s_add_u32 s26, s86, s5
	s_addc_u32 s27, s87, 0
	s_lshl_b32 s5, s2, 7
	s_lshl_b32 s6, s1, 6
	s_add_i32 s6, s6, s5
	v_add_u32_e32 v140, s6, v146
	s_lshl_b32 s7, s4, 12
	v_lshl_add_u32 v136, v140, 1, s7
	v_add_u32_e32 v141, s5, v146
	v_lshlrev_b32_e32 v141, 1, v141
	s_add_i32 s12, s7, 0x800
	v_add_u32_e32 v137, s12, v141
	s_lshl_b32 s12, s4, 10
	v_add_u32_e32 v138, s12, v141
	s_lshl_b32 s12, s38, 10
	v_lshl_add_u32 v134, v146, 2, s12
	v_mov_b32_e32 v135, s12
	v_lshlrev_b32_e32 v147, 2, v146
	v_mov_b32_e32 v130, 0
	s_andn2_b64 vcc, exec, s[34:35]
	s_cbranch_vccnz .Lhs_lb0
	v_mov_b64_e32 v[0:1], s[92:93]
	flat_load_dwordx2 v[0:1], v[0:1] offset:168 sc0 sc1
	s_waitcnt vmcnt(0) lgkmcnt(0)
	v_readfirstlane_b32 s12, v0
	v_readfirstlane_b32 s13, v1
	v_lshlrev_b32_e32 v140, 2, v140
	s_nop 3
	global_load_dword v141, v140, s[12:13]
	global_load_dword v142, v140, s[12:13] offset:2048
	s_waitcnt vmcnt(0)
	v_sub_f32_e32 v141, v141, v142
	v_mul_f32_e32 v141, 0x3fb8aa3b, v141
	v_exp_f32_e32 v141, v141
	s_nop 0
	v_add_f32_e32 v141, 1.0, v141
	v_rcp_f32_e32 v130, v141
	s_nop 0
.Lhs_lb0:
	v_sub_f32_e32 v131, 1.0, v130
	v_mov_b32_e32 v132, 1.0
	s_cmp_eq_u32 s38, 4
	s_cbranch_scc1 .Lhs_init_s
	v_mov_b32_e32 v0, 0
	v_mov_b32_e32 v1, 0
	v_mov_b32_e32 v2, 0
	v_mov_b32_e32 v3, 0
	v_mov_b32_e32 v4, 0
	v_mov_b32_e32 v5, 0
	v_mov_b32_e32 v6, 0
	v_mov_b32_e32 v7, 0
	v_mov_b32_e32 v8, 0
	v_mov_b32_e32 v9, 0
	v_mov_b32_e32 v10, 0
	v_mov_b32_e32 v11, 0
	v_mov_b32_e32 v12, 0
	v_mov_b32_e32 v13, 0
	v_mov_b32_e32 v14, 0
	v_mov_b32_e32 v15, 0
	v_mov_b32_e32 v16, 0
	v_mov_b32_e32 v17, 0
	v_mov_b32_e32 v18, 0
	v_mov_b32_e32 v19, 0
	v_mov_b32_e32 v20, 0
	v_mov_b32_e32 v21, 0
	v_mov_b32_e32 v22, 0
	v_mov_b32_e32 v23, 0
	v_mov_b32_e32 v24, 0
	v_mov_b32_e32 v25, 0
	v_mov_b32_e32 v26, 0
	v_mov_b32_e32 v27, 0
	v_mov_b32_e32 v28, 0
	v_mov_b32_e32 v29, 0
	v_mov_b32_e32 v30, 0
	v_mov_b32_e32 v31, 0
	v_mov_b32_e32 v32, 0
	v_mov_b32_e32 v33, 0
	v_mov_b32_e32 v34, 0
	v_mov_b32_e32 v35, 0
	v_mov_b32_e32 v36, 0
	v_mov_b32_e32 v37, 0
	v_mov_b32_e32 v38, 0
	v_mov_b32_e32 v39, 0
	v_mov_b32_e32 v40, 0
	v_mov_b32_e32 v41, 0
	v_mov_b32_e32 v42, 0
	v_mov_b32_e32 v43, 0
	v_mov_b32_e32 v44, 0
	v_mov_b32_e32 v45, 0
	v_mov_b32_e32 v46, 0
	v_mov_b32_e32 v47, 0
	v_mov_b32_e32 v48, 0
	v_mov_b32_e32 v49, 0
	v_mov_b32_e32 v50, 0
	v_mov_b32_e32 v51, 0
	v_mov_b32_e32 v52, 0
	v_mov_b32_e32 v53, 0
	v_mov_b32_e32 v54, 0
	v_mov_b32_e32 v55, 0
	v_mov_b32_e32 v56, 0
	v_mov_b32_e32 v57, 0
	v_mov_b32_e32 v58, 0
	v_mov_b32_e32 v59, 0
	v_mov_b32_e32 v60, 0
	v_mov_b32_e32 v61, 0
	v_mov_b32_e32 v62, 0
	v_mov_b32_e32 v63, 0
	v_mov_b32_e32 v64, 0
	v_mov_b32_e32 v65, 0
	v_mov_b32_e32 v66, 0
	v_mov_b32_e32 v67, 0
	v_mov_b32_e32 v68, 0
	v_mov_b32_e32 v69, 0
	v_mov_b32_e32 v70, 0
	v_mov_b32_e32 v71, 0
	v_mov_b32_e32 v72, 0
	v_mov_b32_e32 v73, 0
	v_mov_b32_e32 v74, 0
	v_mov_b32_e32 v75, 0
	v_mov_b32_e32 v76, 0
	v_mov_b32_e32 v77, 0
	v_mov_b32_e32 v78, 0
	v_mov_b32_e32 v79, 0
	v_mov_b32_e32 v80, 0
	v_mov_b32_e32 v81, 0
	v_mov_b32_e32 v82, 0
	v_mov_b32_e32 v83, 0
	v_mov_b32_e32 v84, 0
	v_mov_b32_e32 v85, 0
	v_mov_b32_e32 v86, 0
	v_mov_b32_e32 v87, 0
	v_mov_b32_e32 v88, 0
	v_mov_b32_e32 v89, 0
	v_mov_b32_e32 v90, 0
	v_mov_b32_e32 v91, 0
	v_mov_b32_e32 v92, 0
	v_mov_b32_e32 v93, 0
	v_mov_b32_e32 v94, 0
	v_mov_b32_e32 v95, 0
	v_mov_b32_e32 v96, 0
	v_mov_b32_e32 v97, 0
	v_mov_b32_e32 v98, 0
	v_mov_b32_e32 v99, 0
	v_mov_b32_e32 v100, 0
	v_mov_b32_e32 v101, 0
	v_mov_b32_e32 v102, 0
	v_mov_b32_e32 v103, 0
	v_mov_b32_e32 v104, 0
	v_mov_b32_e32 v105, 0
	v_mov_b32_e32 v106, 0
	v_mov_b32_e32 v107, 0
	v_mov_b32_e32 v108, 0
	v_mov_b32_e32 v109, 0
	v_mov_b32_e32 v110, 0
	v_mov_b32_e32 v111, 0
	v_mov_b32_e32 v112, 0
	v_mov_b32_e32 v113, 0
	v_mov_b32_e32 v114, 0
	v_mov_b32_e32 v115, 0
	v_mov_b32_e32 v116, 0
	v_mov_b32_e32 v117, 0
	v_mov_b32_e32 v118, 0
	v_mov_b32_e32 v119, 0
	v_mov_b32_e32 v120, 0
	v_mov_b32_e32 v121, 0
	v_mov_b32_e32 v122, 0
	v_mov_b32_e32 v123, 0
	v_mov_b32_e32 v124, 0
	v_mov_b32_e32 v125, 0
	v_mov_b32_e32 v126, 0
	v_mov_b32_e32 v127, 0
	s_branch .Lhs_go
; #define INP(p, i) ldp((p).tbl, i)
; __device__ void phase_hgrn_scan(const Ctx& p, int l, LAS unsigned char* lds) {
;     ...
;             const size_t so = (((size_t)l * 32 + s) * 4 + h) * 16384 + (size_t)(kh * 64) * 128 + half * 64 + lane;
;             f2 S[32];
;             const float* stp = INP(p, 4) + so;
; #pragma unroll
;             for (int k = 0; k < 32; ++k) S[k] = (f2){stp[(2 * k) * 128], stp[(2 * k + 1) * 128]};
.Lhs_init_s:
	global_load_dword v0, v147, s[30:31] offset:0
	global_load_dword v64, v147, s[30:31] offset:256
	global_load_dword v1, v147, s[30:31] offset:512
	global_load_dword v65, v147, s[30:31] offset:768
	global_load_dword v2, v147, s[30:31] offset:1024
	global_load_dword v66, v147, s[30:31] offset:1280
	global_load_dword v3, v147, s[30:31] offset:1536
	global_load_dword v67, v147, s[30:31] offset:1792
	global_load_dword v4, v147, s[30:31] offset:2048
	global_load_dword v68, v147, s[30:31] offset:2304
	global_load_dword v5, v147, s[30:31] offset:2560
	global_load_dword v69, v147, s[30:31] offset:2816
	global_load_dword v6, v147, s[30:31] offset:3072
	global_load_dword v70, v147, s[30:31] offset:3328
	global_load_dword v7, v147, s[30:31] offset:3584
	global_load_dword v71, v147, s[30:31] offset:3840
	v_add_u32_e32 v147, 0x1000, v147
	global_load_dword v8, v147, s[30:31] offset:0
	global_load_dword v72, v147, s[30:31] offset:256
	global_load_dword v9, v147, s[30:31] offset:512
	global_load_dword v73, v147, s[30:31] offset:768
	global_load_dword v10, v147, s[30:31] offset:1024
	global_load_dword v74, v147, s[30:31] offset:1280
	global_load_dword v11, v147, s[30:31] offset:1536
	global_load_dword v75, v147, s[30:31] offset:1792
	global_load_dword v12, v147, s[30:31] offset:2048
	global_load_dword v76, v147, s[30:31] offset:2304
	global_load_dword v13, v147, s[30:31] offset:2560
	global_load_dword v77, v147, s[30:31] offset:2816
	global_load_dword v14, v147, s[30:31] offset:3072
	global_load_dword v78, v147, s[30:31] offset:3328
	global_load_dword v15, v147, s[30:31] offset:3584
	global_load_dword v79, v147, s[30:31] offset:3840
	v_add_u32_e32 v147, 0x1000, v147
	global_load_dword v16, v147, s[30:31] offset:0
	global_load_dword v80, v147, s[30:31] offset:256
	global_load_dword v17, v147, s[30:31] offset:512
	global_load_dword v81, v147, s[30:31] offset:768
	global_load_dword v18, v147, s[30:31] offset:1024
	global_load_dword v82, v147, s[30:31] offset:1280
	global_load_dword v19, v147, s[30:31] offset:1536
	global_load_dword v83, v147, s[30:31] offset:1792
	global_load_dword v20, v147, s[30:31] offset:2048
	global_load_dword v84, v147, s[30:31] offset:2304
	global_load_dword v21, v147, s[30:31] offset:2560
	global_load_dword v85, v147, s[30:31] offset:2816
	global_load_dword v22, v147, s[30:31] offset:3072
	global_load_dword v86, v147, s[30:31] offset:3328
	global_load_dword v23, v147, s[30:31] offset:3584
	global_load_dword v87, v147, s[30:31] offset:3840
	v_add_u32_e32 v147, 0x1000, v147
	global_load_dword v24, v147, s[30:31] offset:0
	global_load_dword v88, v147, s[30:31] offset:256
	global_load_dword v25, v147, s[30:31] offset:512
	global_load_dword v89, v147, s[30:31] offset:768
	global_load_dword v26, v147, s[30:31] offset:1024
	global_load_dword v90, v147, s[30:31] offset:1280
	global_load_dword v27, v147, s[30:31] offset:1536
	global_load_dword v91, v147, s[30:31] offset:1792
	global_load_dword v28, v147, s[30:31] offset:2048
	global_load_dword v92, v147, s[30:31] offset:2304
	global_load_dword v29, v147, s[30:31] offset:2560
	global_load_dword v93, v147, s[30:31] offset:2816
	global_load_dword v30, v147, s[30:31] offset:3072
	global_load_dword v94, v147, s[30:31] offset:3328
	global_load_dword v31, v147, s[30:31] offset:3584
	global_load_dword v95, v147, s[30:31] offset:3840
	v_add_u32_e32 v147, 0x1000, v147
	global_load_dword v32, v147, s[30:31] offset:0
	global_load_dword v96, v147, s[30:31] offset:256
	global_load_dword v33, v147, s[30:31] offset:512
	global_load_dword v97, v147, s[30:31] offset:768
	global_load_dword v34, v147, s[30:31] offset:1024
	global_load_dword v98, v147, s[30:31] offset:1280
	global_load_dword v35, v147, s[30:31] offset:1536
	global_load_dword v99, v147, s[30:31] offset:1792
	global_load_dword v36, v147, s[30:31] offset:2048
	global_load_dword v100, v147, s[30:31] offset:2304
	global_load_dword v37, v147, s[30:31] offset:2560
	global_load_dword v101, v147, s[30:31] offset:2816
	global_load_dword v38, v147, s[30:31] offset:3072
	global_load_dword v102, v147, s[30:31] offset:3328
	global_load_dword v39, v147, s[30:31] offset:3584
	global_load_dword v103, v147, s[30:31] offset:3840
	v_add_u32_e32 v147, 0x1000, v147
	global_load_dword v40, v147, s[30:31] offset:0
	global_load_dword v104, v147, s[30:31] offset:256
	global_load_dword v41, v147, s[30:31] offset:512
	global_load_dword v105, v147, s[30:31] offset:768
	global_load_dword v42, v147, s[30:31] offset:1024
	global_load_dword v106, v147, s[30:31] offset:1280
	global_load_dword v43, v147, s[30:31] offset:1536
	global_load_dword v107, v147, s[30:31] offset:1792
	global_load_dword v44, v147, s[30:31] offset:2048
	global_load_dword v108, v147, s[30:31] offset:2304
	global_load_dword v45, v147, s[30:31] offset:2560
	global_load_dword v109, v147, s[30:31] offset:2816
	global_load_dword v46, v147, s[30:31] offset:3072
	global_load_dword v110, v147, s[30:31] offset:3328
	global_load_dword v47, v147, s[30:31] offset:3584
	global_load_dword v111, v147, s[30:31] offset:3840
	v_add_u32_e32 v147, 0x1000, v147
	global_load_dword v48, v147, s[30:31] offset:0
	global_load_dword v112, v147, s[30:31] offset:256
	global_load_dword v49, v147, s[30:31] offset:512
	global_load_dword v113, v147, s[30:31] offset:768
	global_load_dword v50, v147, s[30:31] offset:1024
	global_load_dword v114, v147, s[30:31] offset:1280
	global_load_dword v51, v147, s[30:31] offset:1536
	global_load_dword v115, v147, s[30:31] offset:1792
	global_load_dword v52, v147, s[30:31] offset:2048
	global_load_dword v116, v147, s[30:31] offset:2304
	global_load_dword v53, v147, s[30:31] offset:2560
	global_load_dword v117, v147, s[30:31] offset:2816
	global_load_dword v54, v147, s[30:31] offset:3072
	global_load_dword v118, v147, s[30:31] offset:3328
	global_load_dword v55, v147, s[30:31] offset:3584
	global_load_dword v119, v147, s[30:31] offset:3840
	v_add_u32_e32 v147, 0x1000, v147
	global_load_dword v56, v147, s[30:31] offset:0
	global_load_dword v120, v147, s[30:31] offset:256
	global_load_dword v57, v147, s[30:31] offset:512
	global_load_dword v121, v147, s[30:31] offset:768
	global_load_dword v58, v147, s[30:31] offset:1024
	global_load_dword v122, v147, s[30:31] offset:1280
	global_load_dword v59, v147, s[30:31] offset:1536
	global_load_dword v123, v147, s[30:31] offset:1792
	global_load_dword v60, v147, s[30:31] offset:2048
	global_load_dword v124, v147, s[30:31] offset:2304
	global_load_dword v61, v147, s[30:31] offset:2560
	global_load_dword v125, v147, s[30:31] offset:2816
	global_load_dword v62, v147, s[30:31] offset:3072
	global_load_dword v126, v147, s[30:31] offset:3328
	global_load_dword v63, v147, s[30:31] offset:3584
	global_load_dword v127, v147, s[30:31] offset:3840
	v_lshlrev_b32_e32 v147, 2, v146
	s_waitcnt vmcnt(0)
; __device__ __forceinline__ float bf2f(unsigned short b) { return __uint_as_float((unsigned)b << 16); }
; __device__ __forceinline__ void hgrn_scan(const bf16_t* __restrict__ PH, int t0, int nsteps, int h, int half, int kh, int lane, float lb, f2 (&S)[32], float& cp, bf16_t* __restrict__ OHp, float* __restrict__ ckp, LAS float* L) {
;     const bf16_t* row = PH + (size_t)t0 * 2048 + h * 128 + kh * 64 + lane; const int voff = 1024 + (half - kh) * 64;
;     unsigned short q1[3], q2[3], q3[3];
;     { const bf16_t* r = row; q1[0] = r[0]; q1[1] = r[512]; q1[2] = r[voff];
;       r = row + 2048; q2[0] = r[0]; q2[1] = r[512]; q2[2] = r[voff];
;       r = row + 4096; q3[0] = r[0]; q3[1] = r[512]; q3[2] = r[voff]; }
;     const LAS f32x4* pf = (const LAS f32x4*)L;
; #pragma unroll 1
;     for (int s = 0; s < nsteps; ++s) {
;         const float ql = bf2f(q1[0]), fz = bf2f(q1[1]), v = bf2f(q1[2]);
; #pragma unroll
;         for (int j = 0; j < 3; ++j) { q1[j] = q2[j]; q2[j] = q3[j]; }
;         { const bf16_t* r = row + (size_t)(s + 3 < nsteps ? s + 3 : nsteps - 1) * 2048; q3[0] = r[0]; q3[1] = r[512]; q3[2] = r[voff]; }
;         const float fl = lb + (1.0f - lb) * sigm(fz);
;         cp *= fl;
;         if (ckp && (s & 31) == 31 && s < 127) ckp[(s >> 5) * 128 + lane] = cp;
;         L[lane] = fl; L[64 + lane] = ql * sigm(ql);
;         f32x4 F[2][4], Q[2][4];
; #pragma unroll
;         for (int i = 0; i < 4; ++i) { F[0][i] = pf[i]; Q[0][i] = pf[16 + i]; }
;         const f2 v2 = {v, v}; f2 o2 = {0.f, 0.f}, o3 = {0.f, 0.f};
; #pragma unroll
;         for (int g = 0; g < 4; ++g) {
;             if (g < 3) {
; #pragma unroll
;                 for (int i = 0; i < 4; ++i) { F[(g + 1) & 1][i] = pf[(g + 1) * 4 + i]; Q[(g + 1) & 1][i] = pf[16 + (g + 1) * 4 + i]; } }
;             __builtin_amdgcn_sched_barrier(0);
; #pragma unroll
;             for (int i = 0; i < 4; ++i) {
;                 const f32x4 f4 = F[g & 1][i], q4 = Q[g & 1][i]; const int idx = (g * 4 + i) * 2;
;                 const f2 f01 = {f4[0], f4[1]}, f23 = {f4[2], f4[3]}, q01 = {q4[0], q4[1]}, q23 = {q4[2], q4[3]};
;                 S[idx] = pfma(f01, S[idx] - v2, v2); o2 = pfma(S[idx], q01, o2);
;                 S[idx + 1] = pfma(f23, S[idx + 1] - v2, v2); o3 = pfma(S[idx + 1], q23, o3);
;             }
;         }
.Lhs_go:
	global_load_ushort v224, v136, s[24:25]
	global_load_ushort v225, v136, s[24:25] offset:1024
	global_load_ushort v226, v137, s[24:25]
	global_load_ushort v227, v137, s[24:25] offset:128
	v_add_u32_e32 v136, 0x1000, v136
	v_add_u32_e32 v137, 0x1000, v137
	global_load_ushort v228, v136, s[24:25]
	global_load_ushort v229, v136, s[24:25] offset:1024
	global_load_ushort v230, v137, s[24:25]
	global_load_ushort v231, v137, s[24:25] offset:128
	v_add_u32_e32 v136, 0x1000, v136
	v_add_u32_e32 v137, 0x1000, v137
	global_load_ushort v232, v136, s[24:25]
	global_load_ushort v233, v136, s[24:25] offset:1024
	global_load_ushort v234, v137, s[24:25]
	global_load_ushort v235, v137, s[24:25] offset:128
	v_add_u32_e32 v136, 0x1000, v136
	v_add_u32_e32 v137, 0x1000, v137
	global_load_ushort v236, v136, s[24:25]
	global_load_ushort v237, v136, s[24:25] offset:1024
	global_load_ushort v238, v137, s[24:25]
	global_load_ushort v239, v137, s[24:25] offset:128
	v_add_u32_e32 v136, 0x1000, v136
	v_add_u32_e32 v137, 0x1000, v137
	s_waitcnt vmcnt(12)
	v_lshlrev_b32_e32 v140, 16, v225
	v_lshlrev_b32_e32 v141, 16, v224
	v_mul_f32_e32 v142, 0xbfb8aa3b, v140
	v_mul_f32_e32 v143, 0xbfb8aa3b, v141
	v_exp_f32_e32 v142, v142
	v_exp_f32_e32 v143, v143
	v_lshlrev_b32_e32 v250, 16, v226
	v_lshlrev_b32_e32 v251, 16, v227
	v_add_f32_e32 v142, 1.0, v142
	v_add_f32_e32 v143, 1.0, v143
	v_rcp_f32_e32 v142, v142
	v_rcp_f32_e32 v143, v143
	v_fma_f32 v142, v131, v142, v130
	v_mul_f32_e32 v143, v143, v141
	v_mul_f32_e32 v132, v132, v142
	ds_write2st64_b32 v134, v142, v143 offset0:0 offset1:1
	ds_read_b128 v[148:151], v135 offset:0
	ds_read_b128 v[152:155], v135 offset:16
	ds_read_b128 v[156:159], v135 offset:32
	ds_read_b128 v[160:163], v135 offset:48
	ds_read_b128 v[164:167], v135 offset:256
	ds_read_b128 v[168:171], v135 offset:272
	ds_read_b128 v[172:175], v135 offset:288
	ds_read_b128 v[176:179], v135 offset:304
	s_mov_b32 s37, 0
.Lhs_m_loop:
	global_load_ushort v224, v136, s[24:25]
	global_load_ushort v225, v136, s[24:25] offset:1024
	global_load_ushort v226, v137, s[24:25]
	global_load_ushort v227, v137, s[24:25] offset:128
	v_add_u32_e32 v136, 0x1000, v136
	v_add_u32_e32 v137, 0x1000, v137
	ds_read_b128 v[192:195], v135 offset:64
	ds_read_b128 v[196:199], v135 offset:80
	ds_read_b128 v[200:203], v135 offset:96
	ds_read_b128 v[204:207], v135 offset:112
	ds_read_b128 v[208:211], v135 offset:320
	ds_read_b128 v[212:215], v135 offset:336
	ds_read_b128 v[216:219], v135 offset:352
	ds_read_b128 v[220:223], v135 offset:368
	s_waitcnt lgkmcnt(8)
	v_pk_add_f32 v[0:1], v[0:1], v[250:251] op_sel_hi:[1,0] neg_lo:[0,1] neg_hi:[0,1]
	v_pk_add_f32 v[2:3], v[2:3], v[250:251] op_sel_hi:[1,0] neg_lo:[0,1] neg_hi:[0,1]
	v_pk_add_f32 v[4:5], v[4:5], v[250:251] op_sel_hi:[1,0] neg_lo:[0,1] neg_hi:[0,1]
	v_pk_add_f32 v[6:7], v[6:7], v[250:251] op_sel_hi:[1,0] neg_lo:[0,1] neg_hi:[0,1]
	v_pk_fma_f32 v[0:1], v[148:149], v[0:1], v[250:251] op_sel_hi:[1,1,0]
	v_pk_fma_f32 v[2:3], v[150:151], v[2:3], v[250:251] op_sel_hi:[1,1,0]
	v_pk_fma_f32 v[4:5], v[152:153], v[4:5], v[250:251] op_sel_hi:[1,1,0]
	v_pk_fma_f32 v[6:7], v[154:155], v[6:7], v[250:251] op_sel_hi:[1,1,0]
	v_pk_fma_f32 v[240:241], v[0:1], v[164:165], 0 op_sel_hi:[1,1,0]
	v_pk_fma_f32 v[244:245], v[2:3], v[166:167], 0 op_sel_hi:[1,1,0]
	v_pk_fma_f32 v[240:241], v[4:5], v[168:169], v[240:241]
	v_pk_fma_f32 v[244:245], v[6:7], v[170:171], v[244:245]
	v_pk_add_f32 v[8:9], v[8:9], v[250:251] op_sel_hi:[1,0] neg_lo:[0,1] neg_hi:[0,1]
	v_pk_add_f32 v[10:11], v[10:11], v[250:251] op_sel_hi:[1,0] neg_lo:[0,1] neg_hi:[0,1]
	v_pk_add_f32 v[12:13], v[12:13], v[250:251] op_sel_hi:[1,0] neg_lo:[0,1] neg_hi:[0,1]
	v_pk_add_f32 v[14:15], v[14:15], v[250:251] op_sel_hi:[1,0] neg_lo:[0,1] neg_hi:[0,1]
	v_pk_fma_f32 v[8:9], v[156:157], v[8:9], v[250:251] op_sel_hi:[1,1,0]
	v_pk_fma_f32 v[10:11], v[158:159], v[10:11], v[250:251] op_sel_hi:[1,1,0]
	v_pk_fma_f32 v[12:13], v[160:161], v[12:13], v[250:251] op_sel_hi:[1,1,0]
	v_pk_fma_f32 v[14:15], v[162:163], v[14:15], v[250:251] op_sel_hi:[1,1,0]
	v_pk_fma_f32 v[240:241], v[8:9], v[172:173], v[240:241]
	v_pk_fma_f32 v[244:245], v[10:11], v[174:175], v[244:245]
	v_pk_fma_f32 v[240:241], v[12:13], v[176:177], v[240:241]
	v_pk_fma_f32 v[244:245], v[14:15], v[178:179], v[244:245]
	v_pk_add_f32 v[64:65], v[64:65], v[250:251] op_sel:[0,1] op_sel_hi:[1,1] neg_lo:[0,1] neg_hi:[0,1]
	v_pk_add_f32 v[66:67], v[66:67], v[250:251] op_sel:[0,1] op_sel_hi:[1,1] neg_lo:[0,1] neg_hi:[0,1]
	v_pk_add_f32 v[68:69], v[68:69], v[250:251] op_sel:[0,1] op_sel_hi:[1,1] neg_lo:[0,1] neg_hi:[0,1]
	v_pk_add_f32 v[70:71], v[70:71], v[250:251] op_sel:[0,1] op_sel_hi:[1,1] neg_lo:[0,1] neg_hi:[0,1]
	v_pk_fma_f32 v[64:65], v[148:149], v[64:65], v[250:251] op_sel:[0,0,1] op_sel_hi:[1,1,1]
	v_pk_fma_f32 v[66:67], v[150:151], v[66:67], v[250:251] op_sel:[0,0,1] op_sel_hi:[1,1,1]
	v_pk_fma_f32 v[68:69], v[152:153], v[68:69], v[250:251] op_sel:[0,0,1] op_sel_hi:[1,1,1]
	v_pk_fma_f32 v[70:71], v[154:155], v[70:71], v[250:251] op_sel:[0,0,1] op_sel_hi:[1,1,1]
	v_pk_fma_f32 v[246:247], v[64:65], v[164:165], 0 op_sel_hi:[1,1,0]
	v_pk_fma_f32 v[248:249], v[66:67], v[166:167], 0 op_sel_hi:[1,1,0]
	v_pk_fma_f32 v[246:247], v[68:69], v[168:169], v[246:247]
	v_pk_fma_f32 v[248:249], v[70:71], v[170:171], v[248:249]
	v_pk_add_f32 v[72:73], v[72:73], v[250:251] op_sel:[0,1] op_sel_hi:[1,1] neg_lo:[0,1] neg_hi:[0,1]
	v_pk_add_f32 v[74:75], v[74:75], v[250:251] op_sel:[0,1] op_sel_hi:[1,1] neg_lo:[0,1] neg_hi:[0,1]
	v_pk_add_f32 v[76:77], v[76:77], v[250:251] op_sel:[0,1] op_sel_hi:[1,1] neg_lo:[0,1] neg_hi:[0,1]
	v_pk_add_f32 v[78:79], v[78:79], v[250:251] op_sel:[0,1] op_sel_hi:[1,1] neg_lo:[0,1] neg_hi:[0,1]
	v_pk_fma_f32 v[72:73], v[156:157], v[72:73], v[250:251] op_sel:[0,0,1] op_sel_hi:[1,1,1]
	v_pk_fma_f32 v[74:75], v[158:159], v[74:75], v[250:251] op_sel:[0,0,1] op_sel_hi:[1,1,1]
	v_pk_fma_f32 v[76:77], v[160:161], v[76:77], v[250:251] op_sel:[0,0,1] op_sel_hi:[1,1,1]
	v_pk_fma_f32 v[78:79], v[162:163], v[78:79], v[250:251] op_sel:[0,0,1] op_sel_hi:[1,1,1]
	v_pk_fma_f32 v[246:247], v[72:73], v[172:173], v[246:247]
	v_pk_fma_f32 v[248:249], v[74:75], v[174:175], v[248:249]
	v_pk_fma_f32 v[246:247], v[76:77], v[176:177], v[246:247]
	v_pk_fma_f32 v[248:249], v[78:79], v[178:179], v[248:249]
	s_waitcnt vmcnt(12)
; __device__ __forceinline__ float bf2f(unsigned short b) { return __uint_as_float((unsigned)b << 16); }
; __device__ __forceinline__ float sigm(float x) { return __builtin_amdgcn_rcpf(1.0f + __expf(-x)); }
; __device__ __forceinline__ f2 pfma(f2 a, f2 b, f2 c) { return __builtin_elementwise_fma(a, b, c); }
; __device__ __forceinline__ void hgrn_scan(const bf16_t* __restrict__ PH, int t0, int nsteps, int h, int half, int kh, int lane, float lb, f2 (&S)[32], float& cp, bf16_t* __restrict__ OHp, float* __restrict__ ckp, LAS float* L) {
;     ...
;     for (int s = 0; s < nsteps; ++s) {
;         const float ql = bf2f(q1[0]), fz = bf2f(q1[1]), v = bf2f(q1[2]);
; #pragma unroll
;         for (int j = 0; j < 3; ++j) { q1[j] = q2[j]; q2[j] = q3[j]; }
;         { const bf16_t* r = row + (size_t)(s + 3 < nsteps ? s + 3 : nsteps - 1) * 2048; q3[0] = r[0]; q3[1] = r[512]; q3[2] = r[voff]; }
;         const float fl = lb + (1.0f - lb) * sigm(fz);
;         cp *= fl;
;         if (ckp && (s & 31) == 31 && s < 127) ckp[(s >> 5) * 128 + lane] = cp;
;         L[lane] = fl; L[64 + lane] = ql * sigm(ql);
;         f32x4 F[2][4], Q[2][4];
; #pragma unroll
;         for (int i = 0; i < 4; ++i) { F[0][i] = pf[i]; Q[0][i] = pf[16 + i]; }
;         const f2 v2 = {v, v}; f2 o2 = {0.f, 0.f}, o3 = {0.f, 0.f};
; #pragma unroll
;         for (int g = 0; g < 4; ++g) {
;             if (g < 3) {
; #pragma unroll
;                 for (int i = 0; i < 4; ++i) { F[(g + 1) & 1][i] = pf[(g + 1) * 4 + i]; Q[(g + 1) & 1][i] = pf[16 + (g + 1) * 4 + i]; } }
;             __builtin_amdgcn_sched_barrier(0);
; #pragma unroll
;             for (int i = 0; i < 4; ++i) {
;                 const f32x4 f4 = F[g & 1][i], q4 = Q[g & 1][i]; const int idx = (g * 4 + i) * 2;
;                 const f2 f01 = {f4[0], f4[1]}, f23 = {f4[2], f4[3]}, q01 = {q4[0], q4[1]}, q23 = {q4[2], q4[3]};
;                 S[idx] = pfma(f01, S[idx] - v2, v2); o2 = pfma(S[idx], q01, o2);
;                 S[idx + 1] = pfma(f23, S[idx + 1] - v2, v2); o3 = pfma(S[idx + 1], q23, o3);
;             }
;         }
	v_lshlrev_b32_e32 v140, 16, v229
	v_lshlrev_b32_e32 v141, 16, v228
	v_mul_f32_e32 v142, 0xbfb8aa3b, v140
	v_mul_f32_e32 v143, 0xbfb8aa3b, v141
	v_exp_f32_e32 v142, v142
	v_exp_f32_e32 v143, v143
	v_lshlrev_b32_e32 v252, 16, v230
	v_lshlrev_b32_e32 v253, 16, v231
	v_add_f32_e32 v142, 1.0, v142
	v_add_f32_e32 v143, 1.0, v143
	v_rcp_f32_e32 v142, v142
	v_rcp_f32_e32 v143, v143
	v_fma_f32 v142, v131, v142, v130
	v_mul_f32_e32 v143, v143, v141
	v_mul_f32_e32 v132, v132, v142
	ds_write2st64_b32 v134, v142, v143 offset0:2 offset1:3
	ds_read_b128 v[148:151], v135 offset:128
	ds_read_b128 v[152:155], v135 offset:144
	ds_read_b128 v[156:159], v135 offset:160
	ds_read_b128 v[160:163], v135 offset:176
	ds_read_b128 v[164:167], v135 offset:384
	ds_read_b128 v[168:171], v135 offset:400
	ds_read_b128 v[172:175], v135 offset:416
	ds_read_b128 v[176:179], v135 offset:432
	s_waitcnt lgkmcnt(9)
	v_pk_add_f32 v[16:17], v[16:17], v[250:251] op_sel_hi:[1,0] neg_lo:[0,1] neg_hi:[0,1]
	v_pk_add_f32 v[18:19], v[18:19], v[250:251] op_sel_hi:[1,0] neg_lo:[0,1] neg_hi:[0,1]
	v_pk_add_f32 v[20:21], v[20:21], v[250:251] op_sel_hi:[1,0] neg_lo:[0,1] neg_hi:[0,1]
	v_pk_add_f32 v[22:23], v[22:23], v[250:251] op_sel_hi:[1,0] neg_lo:[0,1] neg_hi:[0,1]
	v_pk_fma_f32 v[16:17], v[192:193], v[16:17], v[250:251] op_sel_hi:[1,1,0]
	v_pk_fma_f32 v[18:19], v[194:195], v[18:19], v[250:251] op_sel_hi:[1,1,0]
	v_pk_fma_f32 v[20:21], v[196:197], v[20:21], v[250:251] op_sel_hi:[1,1,0]
	v_pk_fma_f32 v[22:23], v[198:199], v[22:23], v[250:251] op_sel_hi:[1,1,0]
	v_pk_fma_f32 v[240:241], v[16:17], v[208:209], v[240:241]
	v_pk_fma_f32 v[244:245], v[18:19], v[210:211], v[244:245]
	v_pk_fma_f32 v[240:241], v[20:21], v[212:213], v[240:241]
	v_pk_fma_f32 v[244:245], v[22:23], v[214:215], v[244:245]
	v_pk_add_f32 v[24:25], v[24:25], v[250:251] op_sel_hi:[1,0] neg_lo:[0,1] neg_hi:[0,1]
	v_pk_add_f32 v[26:27], v[26:27], v[250:251] op_sel_hi:[1,0] neg_lo:[0,1] neg_hi:[0,1]
	v_pk_add_f32 v[28:29], v[28:29], v[250:251] op_sel_hi:[1,0] neg_lo:[0,1] neg_hi:[0,1]
	v_pk_add_f32 v[30:31], v[30:31], v[250:251] op_sel_hi:[1,0] neg_lo:[0,1] neg_hi:[0,1]
	v_pk_fma_f32 v[24:25], v[200:201], v[24:25], v[250:251] op_sel_hi:[1,1,0]
	v_pk_fma_f32 v[26:27], v[202:203], v[26:27], v[250:251] op_sel_hi:[1,1,0]
	v_pk_fma_f32 v[28:29], v[204:205], v[28:29], v[250:251] op_sel_hi:[1,1,0]
	v_pk_fma_f32 v[30:31], v[206:207], v[30:31], v[250:251] op_sel_hi:[1,1,0]
	v_pk_fma_f32 v[240:241], v[24:25], v[216:217], v[240:241]
	v_pk_fma_f32 v[244:245], v[26:27], v[218:219], v[244:245]
	v_pk_fma_f32 v[240:241], v[28:29], v[220:221], v[240:241]
	v_pk_fma_f32 v[244:245], v[30:31], v[222:223], v[244:245]
	v_pk_add_f32 v[80:81], v[80:81], v[250:251] op_sel:[0,1] op_sel_hi:[1,1] neg_lo:[0,1] neg_hi:[0,1]
	v_pk_add_f32 v[82:83], v[82:83], v[250:251] op_sel:[0,1] op_sel_hi:[1,1] neg_lo:[0,1] neg_hi:[0,1]
	v_pk_add_f32 v[84:85], v[84:85], v[250:251] op_sel:[0,1] op_sel_hi:[1,1] neg_lo:[0,1] neg_hi:[0,1]
	v_pk_add_f32 v[86:87], v[86:87], v[250:251] op_sel:[0,1] op_sel_hi:[1,1] neg_lo:[0,1] neg_hi:[0,1]
	v_pk_fma_f32 v[80:81], v[192:193], v[80:81], v[250:251] op_sel:[0,0,1] op_sel_hi:[1,1,1]
	v_pk_fma_f32 v[82:83], v[194:195], v[82:83], v[250:251] op_sel:[0,0,1] op_sel_hi:[1,1,1]
	v_pk_fma_f32 v[84:85], v[196:197], v[84:85], v[250:251] op_sel:[0,0,1] op_sel_hi:[1,1,1]
	v_pk_fma_f32 v[86:87], v[198:199], v[86:87], v[250:251] op_sel:[0,0,1] op_sel_hi:[1,1,1]
	v_pk_fma_f32 v[246:247], v[80:81], v[208:209], v[246:247]
	v_pk_fma_f32 v[248:249], v[82:83], v[210:211], v[248:249]
	v_pk_fma_f32 v[246:247], v[84:85], v[212:213], v[246:247]
	v_pk_fma_f32 v[248:249], v[86:87], v[214:215], v[248:249]
	v_pk_add_f32 v[88:89], v[88:89], v[250:251] op_sel:[0,1] op_sel_hi:[1,1] neg_lo:[0,1] neg_hi:[0,1]
	v_pk_add_f32 v[90:91], v[90:91], v[250:251] op_sel:[0,1] op_sel_hi:[1,1] neg_lo:[0,1] neg_hi:[0,1]
	v_pk_add_f32 v[92:93], v[92:93], v[250:251] op_sel:[0,1] op_sel_hi:[1,1] neg_lo:[0,1] neg_hi:[0,1]
	v_pk_add_f32 v[94:95], v[94:95], v[250:251] op_sel:[0,1] op_sel_hi:[1,1] neg_lo:[0,1] neg_hi:[0,1]
	v_pk_fma_f32 v[88:89], v[200:201], v[88:89], v[250:251] op_sel:[0,0,1] op_sel_hi:[1,1,1]
	v_pk_fma_f32 v[90:91], v[202:203], v[90:91], v[250:251] op_sel:[0,0,1] op_sel_hi:[1,1,1]
	v_pk_fma_f32 v[92:93], v[204:205], v[92:93], v[250:251] op_sel:[0,0,1] op_sel_hi:[1,1,1]
	v_pk_fma_f32 v[94:95], v[206:207], v[94:95], v[250:251] op_sel:[0,0,1] op_sel_hi:[1,1,1]
	v_pk_fma_f32 v[246:247], v[88:89], v[216:217], v[246:247]
	v_pk_fma_f32 v[248:249], v[90:91], v[218:219], v[248:249]
	v_pk_fma_f32 v[246:247], v[92:93], v[220:221], v[246:247]
	v_pk_fma_f32 v[248:249], v[94:95], v[222:223], v[248:249]
	ds_read_b128 v[192:195], v135 offset:192
	ds_read_b128 v[196:199], v135 offset:208
	ds_read_b128 v[200:203], v135 offset:224
	ds_read_b128 v[204:207], v135 offset:240
	ds_read_b128 v[208:211], v135 offset:448
	ds_read_b128 v[212:215], v135 offset:464
	ds_read_b128 v[216:219], v135 offset:480
	ds_read_b128 v[220:223], v135 offset:496
	s_waitcnt lgkmcnt(8)
; __device__ __forceinline__ f2 pfma(f2 a, f2 b, f2 c) { return __builtin_elementwise_fma(a, b, c); }
; __device__ __forceinline__ void hgrn_scan(const bf16_t* __restrict__ PH, int t0, int nsteps, int h, int half, int kh, int lane, float lb, f2 (&S)[32], float& cp, bf16_t* __restrict__ OHp, float* __restrict__ ckp, LAS float* L) {
;     ...
;         for (int g = 0; g < 4; ++g) {
;             if (g < 3) {
; #pragma unroll
;                 for (int i = 0; i < 4; ++i) { F[(g + 1) & 1][i] = pf[(g + 1) * 4 + i]; Q[(g + 1) & 1][i] = pf[16 + (g + 1) * 4 + i]; } }
;             __builtin_amdgcn_sched_barrier(0);
; #pragma unroll
;             for (int i = 0; i < 4; ++i) {
;                 const f32x4 f4 = F[g & 1][i], q4 = Q[g & 1][i]; const int idx = (g * 4 + i) * 2;
;                 const f2 f01 = {f4[0], f4[1]}, f23 = {f4[2], f4[3]}, q01 = {q4[0], q4[1]}, q23 = {q4[2], q4[3]};
;                 S[idx] = pfma(f01, S[idx] - v2, v2); o2 = pfma(S[idx], q01, o2);
;                 S[idx + 1] = pfma(f23, S[idx + 1] - v2, v2); o3 = pfma(S[idx + 1], q23, o3);
;             }
	v_pk_add_f32 v[32:33], v[32:33], v[250:251] op_sel_hi:[1,0] neg_lo:[0,1] neg_hi:[0,1]
	v_pk_add_f32 v[34:35], v[34:35], v[250:251] op_sel_hi:[1,0] neg_lo:[0,1] neg_hi:[0,1]
	v_pk_add_f32 v[36:37], v[36:37], v[250:251] op_sel_hi:[1,0] neg_lo:[0,1] neg_hi:[0,1]
	v_pk_add_f32 v[38:39], v[38:39], v[250:251] op_sel_hi:[1,0] neg_lo:[0,1] neg_hi:[0,1]
	v_pk_fma_f32 v[32:33], v[148:149], v[32:33], v[250:251] op_sel_hi:[1,1,0]
	v_pk_fma_f32 v[34:35], v[150:151], v[34:35], v[250:251] op_sel_hi:[1,1,0]
	v_pk_fma_f32 v[36:37], v[152:153], v[36:37], v[250:251] op_sel_hi:[1,1,0]
	v_pk_fma_f32 v[38:39], v[154:155], v[38:39], v[250:251] op_sel_hi:[1,1,0]
	v_pk_fma_f32 v[240:241], v[32:33], v[164:165], v[240:241]
	v_pk_fma_f32 v[244:245], v[34:35], v[166:167], v[244:245]
	v_pk_fma_f32 v[240:241], v[36:37], v[168:169], v[240:241]
	v_pk_fma_f32 v[244:245], v[38:39], v[170:171], v[244:245]
	v_pk_add_f32 v[40:41], v[40:41], v[250:251] op_sel_hi:[1,0] neg_lo:[0,1] neg_hi:[0,1]
	v_pk_add_f32 v[42:43], v[42:43], v[250:251] op_sel_hi:[1,0] neg_lo:[0,1] neg_hi:[0,1]
	v_pk_add_f32 v[44:45], v[44:45], v[250:251] op_sel_hi:[1,0] neg_lo:[0,1] neg_hi:[0,1]
	v_pk_add_f32 v[46:47], v[46:47], v[250:251] op_sel_hi:[1,0] neg_lo:[0,1] neg_hi:[0,1]
	v_pk_fma_f32 v[40:41], v[156:157], v[40:41], v[250:251] op_sel_hi:[1,1,0]
	v_pk_fma_f32 v[42:43], v[158:159], v[42:43], v[250:251] op_sel_hi:[1,1,0]
	v_pk_fma_f32 v[44:45], v[160:161], v[44:45], v[250:251] op_sel_hi:[1,1,0]
	v_pk_fma_f32 v[46:47], v[162:163], v[46:47], v[250:251] op_sel_hi:[1,1,0]
	v_pk_fma_f32 v[240:241], v[40:41], v[172:173], v[240:241]
	v_pk_fma_f32 v[244:245], v[42:43], v[174:175], v[244:245]
	v_pk_fma_f32 v[240:241], v[44:45], v[176:177], v[240:241]
	v_pk_fma_f32 v[244:245], v[46:47], v[178:179], v[244:245]
	v_pk_add_f32 v[96:97], v[96:97], v[250:251] op_sel:[0,1] op_sel_hi:[1,1] neg_lo:[0,1] neg_hi:[0,1]
	v_pk_add_f32 v[98:99], v[98:99], v[250:251] op_sel:[0,1] op_sel_hi:[1,1] neg_lo:[0,1] neg_hi:[0,1]
	v_pk_add_f32 v[100:101], v[100:101], v[250:251] op_sel:[0,1] op_sel_hi:[1,1] neg_lo:[0,1] neg_hi:[0,1]
	v_pk_add_f32 v[102:103], v[102:103], v[250:251] op_sel:[0,1] op_sel_hi:[1,1] neg_lo:[0,1] neg_hi:[0,1]
	v_pk_fma_f32 v[96:97], v[148:149], v[96:97], v[250:251] op_sel:[0,0,1] op_sel_hi:[1,1,1]
	v_pk_fma_f32 v[98:99], v[150:151], v[98:99], v[250:251] op_sel:[0,0,1] op_sel_hi:[1,1,1]
	v_pk_fma_f32 v[100:101], v[152:153], v[100:101], v[250:251] op_sel:[0,0,1] op_sel_hi:[1,1,1]
	v_pk_fma_f32 v[102:103], v[154:155], v[102:103], v[250:251] op_sel:[0,0,1] op_sel_hi:[1,1,1]
	v_pk_fma_f32 v[246:247], v[96:97], v[164:165], v[246:247]
	v_pk_fma_f32 v[248:249], v[98:99], v[166:167], v[248:249]
	v_pk_fma_f32 v[246:247], v[100:101], v[168:169], v[246:247]
	v_pk_fma_f32 v[248:249], v[102:103], v[170:171], v[248:249]
	v_pk_add_f32 v[104:105], v[104:105], v[250:251] op_sel:[0,1] op_sel_hi:[1,1] neg_lo:[0,1] neg_hi:[0,1]
	v_pk_add_f32 v[106:107], v[106:107], v[250:251] op_sel:[0,1] op_sel_hi:[1,1] neg_lo:[0,1] neg_hi:[0,1]
	v_pk_add_f32 v[108:109], v[108:109], v[250:251] op_sel:[0,1] op_sel_hi:[1,1] neg_lo:[0,1] neg_hi:[0,1]
	v_pk_add_f32 v[110:111], v[110:111], v[250:251] op_sel:[0,1] op_sel_hi:[1,1] neg_lo:[0,1] neg_hi:[0,1]
	v_pk_fma_f32 v[104:105], v[156:157], v[104:105], v[250:251] op_sel:[0,0,1] op_sel_hi:[1,1,1]
	v_pk_fma_f32 v[106:107], v[158:159], v[106:107], v[250:251] op_sel:[0,0,1] op_sel_hi:[1,1,1]
	v_pk_fma_f32 v[108:109], v[160:161], v[108:109], v[250:251] op_sel:[0,0,1] op_sel_hi:[1,1,1]
	v_pk_fma_f32 v[110:111], v[162:163], v[110:111], v[250:251] op_sel:[0,0,1] op_sel_hi:[1,1,1]
	v_pk_fma_f32 v[246:247], v[104:105], v[172:173], v[246:247]
	v_pk_fma_f32 v[248:249], v[106:107], v[174:175], v[248:249]
	v_pk_fma_f32 v[246:247], v[108:109], v[176:177], v[246:247]
	v_pk_fma_f32 v[248:249], v[110:111], v[178:179], v[248:249]
	ds_read_b128 v[148:151], v135 offset:512
	ds_read_b128 v[152:155], v135 offset:528
	ds_read_b128 v[156:159], v135 offset:544
	ds_read_b128 v[160:163], v135 offset:560
	ds_read_b128 v[164:167], v135 offset:768
	ds_read_b128 v[168:171], v135 offset:784
	ds_read_b128 v[172:175], v135 offset:800
	ds_read_b128 v[176:179], v135 offset:816
	s_waitcnt lgkmcnt(8)
	v_pk_add_f32 v[48:49], v[48:49], v[250:251] op_sel_hi:[1,0] neg_lo:[0,1] neg_hi:[0,1]
	v_pk_add_f32 v[50:51], v[50:51], v[250:251] op_sel_hi:[1,0] neg_lo:[0,1] neg_hi:[0,1]
	v_pk_add_f32 v[52:53], v[52:53], v[250:251] op_sel_hi:[1,0] neg_lo:[0,1] neg_hi:[0,1]
	v_pk_add_f32 v[54:55], v[54:55], v[250:251] op_sel_hi:[1,0] neg_lo:[0,1] neg_hi:[0,1]
	v_pk_fma_f32 v[48:49], v[192:193], v[48:49], v[250:251] op_sel_hi:[1,1,0]
	v_pk_fma_f32 v[50:51], v[194:195], v[50:51], v[250:251] op_sel_hi:[1,1,0]
	v_pk_fma_f32 v[52:53], v[196:197], v[52:53], v[250:251] op_sel_hi:[1,1,0]
	v_pk_fma_f32 v[54:55], v[198:199], v[54:55], v[250:251] op_sel_hi:[1,1,0]
	v_pk_fma_f32 v[240:241], v[48:49], v[208:209], v[240:241]
	v_pk_fma_f32 v[244:245], v[50:51], v[210:211], v[244:245]
	v_pk_fma_f32 v[240:241], v[52:53], v[212:213], v[240:241]
	v_pk_fma_f32 v[244:245], v[54:55], v[214:215], v[244:245]
	v_pk_add_f32 v[56:57], v[56:57], v[250:251] op_sel_hi:[1,0] neg_lo:[0,1] neg_hi:[0,1]
	v_pk_add_f32 v[58:59], v[58:59], v[250:251] op_sel_hi:[1,0] neg_lo:[0,1] neg_hi:[0,1]
	v_pk_add_f32 v[60:61], v[60:61], v[250:251] op_sel_hi:[1,0] neg_lo:[0,1] neg_hi:[0,1]
	v_pk_add_f32 v[62:63], v[62:63], v[250:251] op_sel_hi:[1,0] neg_lo:[0,1] neg_hi:[0,1]
	v_pk_fma_f32 v[56:57], v[200:201], v[56:57], v[250:251] op_sel_hi:[1,1,0]
	v_pk_fma_f32 v[58:59], v[202:203], v[58:59], v[250:251] op_sel_hi:[1,1,0]
	v_pk_fma_f32 v[60:61], v[204:205], v[60:61], v[250:251] op_sel_hi:[1,1,0]
; __device__ __forceinline__ float bf2f(unsigned short b) { return __uint_as_float((unsigned)b << 16); }
; __device__ __forceinline__ unsigned short f2bf(float f) { unsigned u = __float_as_uint(f); u += 0x7FFFu + ((u >> 16) & 1u); return (unsigned short)(u >> 16); }
; __device__ __forceinline__ float sigm(float x) { return __builtin_amdgcn_rcpf(1.0f + __expf(-x)); }
; __device__ __forceinline__ f2 pfma(f2 a, f2 b, f2 c) { return __builtin_elementwise_fma(a, b, c); }
; __device__ __forceinline__ void hgrn_scan(const bf16_t* __restrict__ PH, int t0, int nsteps, int h, int half, int kh, int lane, float lb, f2 (&S)[32], float& cp, bf16_t* __restrict__ OHp, float* __restrict__ ckp, LAS float* L) {
;     ...
;     for (int s = 0; s < nsteps; ++s) {
;         const float ql = bf2f(q1[0]), fz = bf2f(q1[1]), v = bf2f(q1[2]);
; #pragma unroll
;         for (int j = 0; j < 3; ++j) { q1[j] = q2[j]; q2[j] = q3[j]; }
;         { const bf16_t* r = row + (size_t)(s + 3 < nsteps ? s + 3 : nsteps - 1) * 2048; q3[0] = r[0]; q3[1] = r[512]; q3[2] = r[voff]; }
;         const float fl = lb + (1.0f - lb) * sigm(fz);
;         cp *= fl;
;         if (ckp && (s & 31) == 31 && s < 127) ckp[(s >> 5) * 128 + lane] = cp;
;         L[lane] = fl; L[64 + lane] = ql * sigm(ql);
;         f32x4 F[2][4], Q[2][4];
; #pragma unroll
;         for (int i = 0; i < 4; ++i) { F[0][i] = pf[i]; Q[0][i] = pf[16 + i]; }
;         const f2 v2 = {v, v}; f2 o2 = {0.f, 0.f}, o3 = {0.f, 0.f};
; #pragma unroll
;         for (int g = 0; g < 4; ++g) {
;             if (g < 3) {
; #pragma unroll
;                 for (int i = 0; i < 4; ++i) { F[(g + 1) & 1][i] = pf[(g + 1) * 4 + i]; Q[(g + 1) & 1][i] = pf[16 + (g + 1) * 4 + i]; } }
;             __builtin_amdgcn_sched_barrier(0);
; #pragma unroll
;             for (int i = 0; i < 4; ++i) {
;                 const f32x4 f4 = F[g & 1][i], q4 = Q[g & 1][i]; const int idx = (g * 4 + i) * 2;
;                 const f2 f01 = {f4[0], f4[1]}, f23 = {f4[2], f4[3]}, q01 = {q4[0], q4[1]}, q23 = {q4[2], q4[3]};
;                 S[idx] = pfma(f01, S[idx] - v2, v2); o2 = pfma(S[idx], q01, o2);
;                 S[idx + 1] = pfma(f23, S[idx + 1] - v2, v2); o3 = pfma(S[idx + 1], q23, o3);
;             }
;         }
;         OHp[(size_t)(t0 + s) * 512 + h * 128 + half * 64 + lane] = f2bf((o2[0] + o2[1]) + (o3[0] + o3[1]));
	v_pk_fma_f32 v[62:63], v[206:207], v[62:63], v[250:251] op_sel_hi:[1,1,0]
	v_pk_fma_f32 v[240:241], v[56:57], v[216:217], v[240:241]
	v_pk_fma_f32 v[244:245], v[58:59], v[218:219], v[244:245]
	v_pk_fma_f32 v[240:241], v[60:61], v[220:221], v[240:241]
	v_pk_fma_f32 v[244:245], v[62:63], v[222:223], v[244:245]
	v_pk_add_f32 v[112:113], v[112:113], v[250:251] op_sel:[0,1] op_sel_hi:[1,1] neg_lo:[0,1] neg_hi:[0,1]
	v_pk_add_f32 v[114:115], v[114:115], v[250:251] op_sel:[0,1] op_sel_hi:[1,1] neg_lo:[0,1] neg_hi:[0,1]
	v_pk_add_f32 v[116:117], v[116:117], v[250:251] op_sel:[0,1] op_sel_hi:[1,1] neg_lo:[0,1] neg_hi:[0,1]
	v_pk_add_f32 v[118:119], v[118:119], v[250:251] op_sel:[0,1] op_sel_hi:[1,1] neg_lo:[0,1] neg_hi:[0,1]
	v_pk_fma_f32 v[112:113], v[192:193], v[112:113], v[250:251] op_sel:[0,0,1] op_sel_hi:[1,1,1]
	v_pk_fma_f32 v[114:115], v[194:195], v[114:115], v[250:251] op_sel:[0,0,1] op_sel_hi:[1,1,1]
	v_pk_fma_f32 v[116:117], v[196:197], v[116:117], v[250:251] op_sel:[0,0,1] op_sel_hi:[1,1,1]
	v_pk_fma_f32 v[118:119], v[198:199], v[118:119], v[250:251] op_sel:[0,0,1] op_sel_hi:[1,1,1]
	v_pk_fma_f32 v[246:247], v[112:113], v[208:209], v[246:247]
	v_pk_fma_f32 v[248:249], v[114:115], v[210:211], v[248:249]
	v_pk_fma_f32 v[246:247], v[116:117], v[212:213], v[246:247]
	v_pk_fma_f32 v[248:249], v[118:119], v[214:215], v[248:249]
	v_pk_add_f32 v[120:121], v[120:121], v[250:251] op_sel:[0,1] op_sel_hi:[1,1] neg_lo:[0,1] neg_hi:[0,1]
	v_pk_add_f32 v[122:123], v[122:123], v[250:251] op_sel:[0,1] op_sel_hi:[1,1] neg_lo:[0,1] neg_hi:[0,1]
	v_pk_add_f32 v[124:125], v[124:125], v[250:251] op_sel:[0,1] op_sel_hi:[1,1] neg_lo:[0,1] neg_hi:[0,1]
	v_pk_add_f32 v[126:127], v[126:127], v[250:251] op_sel:[0,1] op_sel_hi:[1,1] neg_lo:[0,1] neg_hi:[0,1]
	v_pk_fma_f32 v[120:121], v[200:201], v[120:121], v[250:251] op_sel:[0,0,1] op_sel_hi:[1,1,1]
	v_pk_fma_f32 v[122:123], v[202:203], v[122:123], v[250:251] op_sel:[0,0,1] op_sel_hi:[1,1,1]
	v_pk_fma_f32 v[124:125], v[204:205], v[124:125], v[250:251] op_sel:[0,0,1] op_sel_hi:[1,1,1]
	v_pk_fma_f32 v[126:127], v[206:207], v[126:127], v[250:251] op_sel:[0,0,1] op_sel_hi:[1,1,1]
	v_pk_fma_f32 v[246:247], v[120:121], v[216:217], v[246:247]
	v_pk_fma_f32 v[248:249], v[122:123], v[218:219], v[248:249]
	v_pk_fma_f32 v[246:247], v[124:125], v[220:221], v[246:247]
	v_pk_fma_f32 v[248:249], v[126:127], v[222:223], v[248:249]
	v_add_f32_e32 v240, v240, v241
	v_add_f32_e32 v244, v244, v245
	v_add_f32_e32 v240, v240, v244
	v_bfe_u32 v244, v240, 16, 1
	v_add3_u32 v240, v240, v244, s69
	global_store_short_d16_hi v138, v240, s[26:27]
	v_add_f32_e32 v246, v246, v247
	v_add_f32_e32 v248, v248, v249
	v_add_f32_e32 v246, v246, v248
	v_bfe_u32 v248, v246, 16, 1
	v_add3_u32 v246, v246, v248, s69
	global_store_short_d16_hi v138, v246, s[26:27] offset:128
	v_mov_b32_e32 v250, v252
	v_mov_b32_e32 v251, v253
	v_add_u32_e32 v138, 0x400, v138
	global_load_ushort v228, v136, s[24:25]
	global_load_ushort v229, v136, s[24:25] offset:1024
	global_load_ushort v230, v137, s[24:25]
	global_load_ushort v231, v137, s[24:25] offset:128
	v_add_u32_e32 v136, 0x1000, v136
	v_add_u32_e32 v137, 0x1000, v137
	ds_read_b128 v[192:195], v135 offset:576
	ds_read_b128 v[196:199], v135 offset:592
	ds_read_b128 v[200:203], v135 offset:608
	ds_read_b128 v[204:207], v135 offset:624
	ds_read_b128 v[208:211], v135 offset:832
	ds_read_b128 v[212:215], v135 offset:848
	ds_read_b128 v[216:219], v135 offset:864
	ds_read_b128 v[220:223], v135 offset:880
	s_waitcnt lgkmcnt(8)
	v_pk_add_f32 v[0:1], v[0:1], v[250:251] op_sel_hi:[1,0] neg_lo:[0,1] neg_hi:[0,1]
	v_pk_add_f32 v[2:3], v[2:3], v[250:251] op_sel_hi:[1,0] neg_lo:[0,1] neg_hi:[0,1]
	v_pk_add_f32 v[4:5], v[4:5], v[250:251] op_sel_hi:[1,0] neg_lo:[0,1] neg_hi:[0,1]
	v_pk_add_f32 v[6:7], v[6:7], v[250:251] op_sel_hi:[1,0] neg_lo:[0,1] neg_hi:[0,1]
	v_pk_fma_f32 v[0:1], v[148:149], v[0:1], v[250:251] op_sel_hi:[1,1,0]
	v_pk_fma_f32 v[2:3], v[150:151], v[2:3], v[250:251] op_sel_hi:[1,1,0]
	v_pk_fma_f32 v[4:5], v[152:153], v[4:5], v[250:251] op_sel_hi:[1,1,0]
	v_pk_fma_f32 v[6:7], v[154:155], v[6:7], v[250:251] op_sel_hi:[1,1,0]
	v_pk_fma_f32 v[240:241], v[0:1], v[164:165], 0 op_sel_hi:[1,1,0]
	v_pk_fma_f32 v[244:245], v[2:3], v[166:167], 0 op_sel_hi:[1,1,0]
	v_pk_fma_f32 v[240:241], v[4:5], v[168:169], v[240:241]
	v_pk_fma_f32 v[244:245], v[6:7], v[170:171], v[244:245]
	v_pk_add_f32 v[8:9], v[8:9], v[250:251] op_sel_hi:[1,0] neg_lo:[0,1] neg_hi:[0,1]
	v_pk_add_f32 v[10:11], v[10:11], v[250:251] op_sel_hi:[1,0] neg_lo:[0,1] neg_hi:[0,1]
	v_pk_add_f32 v[12:13], v[12:13], v[250:251] op_sel_hi:[1,0] neg_lo:[0,1] neg_hi:[0,1]
	v_pk_add_f32 v[14:15], v[14:15], v[250:251] op_sel_hi:[1,0] neg_lo:[0,1] neg_hi:[0,1]
	v_pk_fma_f32 v[8:9], v[156:157], v[8:9], v[250:251] op_sel_hi:[1,1,0]
	v_pk_fma_f32 v[10:11], v[158:159], v[10:11], v[250:251] op_sel_hi:[1,1,0]
	v_pk_fma_f32 v[12:13], v[160:161], v[12:13], v[250:251] op_sel_hi:[1,1,0]
	v_pk_fma_f32 v[14:15], v[162:163], v[14:15], v[250:251] op_sel_hi:[1,1,0]
	v_pk_fma_f32 v[240:241], v[8:9], v[172:173], v[240:241]
	v_pk_fma_f32 v[244:245], v[10:11], v[174:175], v[244:245]
	v_pk_fma_f32 v[240:241], v[12:13], v[176:177], v[240:241]
	v_pk_fma_f32 v[244:245], v[14:15], v[178:179], v[244:245]
	v_pk_add_f32 v[64:65], v[64:65], v[250:251] op_sel:[0,1] op_sel_hi:[1,1] neg_lo:[0,1] neg_hi:[0,1]
	v_pk_add_f32 v[66:67], v[66:67], v[250:251] op_sel:[0,1] op_sel_hi:[1,1] neg_lo:[0,1] neg_hi:[0,1]
	v_pk_add_f32 v[68:69], v[68:69], v[250:251] op_sel:[0,1] op_sel_hi:[1,1] neg_lo:[0,1] neg_hi:[0,1]
	v_pk_add_f32 v[70:71], v[70:71], v[250:251] op_sel:[0,1] op_sel_hi:[1,1] neg_lo:[0,1] neg_hi:[0,1]
; __device__ __forceinline__ float bf2f(unsigned short b) { return __uint_as_float((unsigned)b << 16); }
; __device__ __forceinline__ float sigm(float x) { return __builtin_amdgcn_rcpf(1.0f + __expf(-x)); }
; __device__ __forceinline__ f2 pfma(f2 a, f2 b, f2 c) { return __builtin_elementwise_fma(a, b, c); }
; __device__ __forceinline__ void hgrn_scan(const bf16_t* __restrict__ PH, int t0, int nsteps, int h, int half, int kh, int lane, float lb, f2 (&S)[32], float& cp, bf16_t* __restrict__ OHp, float* __restrict__ ckp, LAS float* L) {
;     ...
;     for (int s = 0; s < nsteps; ++s) {
;         const float ql = bf2f(q1[0]), fz = bf2f(q1[1]), v = bf2f(q1[2]);
; #pragma unroll
;         for (int j = 0; j < 3; ++j) { q1[j] = q2[j]; q2[j] = q3[j]; }
;         { const bf16_t* r = row + (size_t)(s + 3 < nsteps ? s + 3 : nsteps - 1) * 2048; q3[0] = r[0]; q3[1] = r[512]; q3[2] = r[voff]; }
;         const float fl = lb + (1.0f - lb) * sigm(fz);
;         cp *= fl;
;         if (ckp && (s & 31) == 31 && s < 127) ckp[(s >> 5) * 128 + lane] = cp;
;         L[lane] = fl; L[64 + lane] = ql * sigm(ql);
;         f32x4 F[2][4], Q[2][4];
; #pragma unroll
;         for (int i = 0; i < 4; ++i) { F[0][i] = pf[i]; Q[0][i] = pf[16 + i]; }
;         const f2 v2 = {v, v}; f2 o2 = {0.f, 0.f}, o3 = {0.f, 0.f};
; #pragma unroll
;         for (int g = 0; g < 4; ++g) {
;             if (g < 3) {
; #pragma unroll
;                 for (int i = 0; i < 4; ++i) { F[(g + 1) & 1][i] = pf[(g + 1) * 4 + i]; Q[(g + 1) & 1][i] = pf[16 + (g + 1) * 4 + i]; } }
;             __builtin_amdgcn_sched_barrier(0);
; #pragma unroll
;             for (int i = 0; i < 4; ++i) {
;                 const f32x4 f4 = F[g & 1][i], q4 = Q[g & 1][i]; const int idx = (g * 4 + i) * 2;
;                 const f2 f01 = {f4[0], f4[1]}, f23 = {f4[2], f4[3]}, q01 = {q4[0], q4[1]}, q23 = {q4[2], q4[3]};
;                 S[idx] = pfma(f01, S[idx] - v2, v2); o2 = pfma(S[idx], q01, o2);
;                 S[idx + 1] = pfma(f23, S[idx + 1] - v2, v2); o3 = pfma(S[idx + 1], q23, o3);
;             }
	v_pk_fma_f32 v[64:65], v[148:149], v[64:65], v[250:251] op_sel:[0,0,1] op_sel_hi:[1,1,1]
	v_pk_fma_f32 v[66:67], v[150:151], v[66:67], v[250:251] op_sel:[0,0,1] op_sel_hi:[1,1,1]
	v_pk_fma_f32 v[68:69], v[152:153], v[68:69], v[250:251] op_sel:[0,0,1] op_sel_hi:[1,1,1]
	v_pk_fma_f32 v[70:71], v[154:155], v[70:71], v[250:251] op_sel:[0,0,1] op_sel_hi:[1,1,1]
	v_pk_fma_f32 v[246:247], v[64:65], v[164:165], 0 op_sel_hi:[1,1,0]
	v_pk_fma_f32 v[248:249], v[66:67], v[166:167], 0 op_sel_hi:[1,1,0]
	v_pk_fma_f32 v[246:247], v[68:69], v[168:169], v[246:247]
	v_pk_fma_f32 v[248:249], v[70:71], v[170:171], v[248:249]
	v_pk_add_f32 v[72:73], v[72:73], v[250:251] op_sel:[0,1] op_sel_hi:[1,1] neg_lo:[0,1] neg_hi:[0,1]
	v_pk_add_f32 v[74:75], v[74:75], v[250:251] op_sel:[0,1] op_sel_hi:[1,1] neg_lo:[0,1] neg_hi:[0,1]
	v_pk_add_f32 v[76:77], v[76:77], v[250:251] op_sel:[0,1] op_sel_hi:[1,1] neg_lo:[0,1] neg_hi:[0,1]
	v_pk_add_f32 v[78:79], v[78:79], v[250:251] op_sel:[0,1] op_sel_hi:[1,1] neg_lo:[0,1] neg_hi:[0,1]
	v_pk_fma_f32 v[72:73], v[156:157], v[72:73], v[250:251] op_sel:[0,0,1] op_sel_hi:[1,1,1]
	v_pk_fma_f32 v[74:75], v[158:159], v[74:75], v[250:251] op_sel:[0,0,1] op_sel_hi:[1,1,1]
	v_pk_fma_f32 v[76:77], v[160:161], v[76:77], v[250:251] op_sel:[0,0,1] op_sel_hi:[1,1,1]
	v_pk_fma_f32 v[78:79], v[162:163], v[78:79], v[250:251] op_sel:[0,0,1] op_sel_hi:[1,1,1]
	v_pk_fma_f32 v[246:247], v[72:73], v[172:173], v[246:247]
	v_pk_fma_f32 v[248:249], v[74:75], v[174:175], v[248:249]
	v_pk_fma_f32 v[246:247], v[76:77], v[176:177], v[246:247]
	v_pk_fma_f32 v[248:249], v[78:79], v[178:179], v[248:249]
	s_waitcnt vmcnt(14)
	v_lshlrev_b32_e32 v140, 16, v233
	v_lshlrev_b32_e32 v141, 16, v232
	v_mul_f32_e32 v142, 0xbfb8aa3b, v140
	v_mul_f32_e32 v143, 0xbfb8aa3b, v141
	v_exp_f32_e32 v142, v142
	v_exp_f32_e32 v143, v143
	v_lshlrev_b32_e32 v252, 16, v234
	v_lshlrev_b32_e32 v253, 16, v235
	v_add_f32_e32 v142, 1.0, v142
	v_add_f32_e32 v143, 1.0, v143
	v_rcp_f32_e32 v142, v142
	v_rcp_f32_e32 v143, v143
	v_fma_f32 v142, v131, v142, v130
	v_mul_f32_e32 v143, v143, v141
	v_mul_f32_e32 v132, v132, v142
	ds_write2st64_b32 v134, v142, v143 offset0:0 offset1:1
	ds_read_b128 v[148:151], v135 offset:640
	ds_read_b128 v[152:155], v135 offset:656
	ds_read_b128 v[156:159], v135 offset:672
	ds_read_b128 v[160:163], v135 offset:688
	ds_read_b128 v[164:167], v135 offset:896
	ds_read_b128 v[168:171], v135 offset:912
	ds_read_b128 v[172:175], v135 offset:928
	ds_read_b128 v[176:179], v135 offset:944
	s_waitcnt lgkmcnt(9)
	v_pk_add_f32 v[16:17], v[16:17], v[250:251] op_sel_hi:[1,0] neg_lo:[0,1] neg_hi:[0,1]
	v_pk_add_f32 v[18:19], v[18:19], v[250:251] op_sel_hi:[1,0] neg_lo:[0,1] neg_hi:[0,1]
	v_pk_add_f32 v[20:21], v[20:21], v[250:251] op_sel_hi:[1,0] neg_lo:[0,1] neg_hi:[0,1]
	v_pk_add_f32 v[22:23], v[22:23], v[250:251] op_sel_hi:[1,0] neg_lo:[0,1] neg_hi:[0,1]
	v_pk_fma_f32 v[16:17], v[192:193], v[16:17], v[250:251] op_sel_hi:[1,1,0]
	v_pk_fma_f32 v[18:19], v[194:195], v[18:19], v[250:251] op_sel_hi:[1,1,0]
	v_pk_fma_f32 v[20:21], v[196:197], v[20:21], v[250:251] op_sel_hi:[1,1,0]
	v_pk_fma_f32 v[22:23], v[198:199], v[22:23], v[250:251] op_sel_hi:[1,1,0]
	v_pk_fma_f32 v[240:241], v[16:17], v[208:209], v[240:241]
	v_pk_fma_f32 v[244:245], v[18:19], v[210:211], v[244:245]
	v_pk_fma_f32 v[240:241], v[20:21], v[212:213], v[240:241]
	v_pk_fma_f32 v[244:245], v[22:23], v[214:215], v[244:245]
	v_pk_add_f32 v[24:25], v[24:25], v[250:251] op_sel_hi:[1,0] neg_lo:[0,1] neg_hi:[0,1]
	v_pk_add_f32 v[26:27], v[26:27], v[250:251] op_sel_hi:[1,0] neg_lo:[0,1] neg_hi:[0,1]
	v_pk_add_f32 v[28:29], v[28:29], v[250:251] op_sel_hi:[1,0] neg_lo:[0,1] neg_hi:[0,1]
	v_pk_add_f32 v[30:31], v[30:31], v[250:251] op_sel_hi:[1,0] neg_lo:[0,1] neg_hi:[0,1]
	v_pk_fma_f32 v[24:25], v[200:201], v[24:25], v[250:251] op_sel_hi:[1,1,0]
	v_pk_fma_f32 v[26:27], v[202:203], v[26:27], v[250:251] op_sel_hi:[1,1,0]
	v_pk_fma_f32 v[28:29], v[204:205], v[28:29], v[250:251] op_sel_hi:[1,1,0]
	v_pk_fma_f32 v[30:31], v[206:207], v[30:31], v[250:251] op_sel_hi:[1,1,0]
	v_pk_fma_f32 v[240:241], v[24:25], v[216:217], v[240:241]
	v_pk_fma_f32 v[244:245], v[26:27], v[218:219], v[244:245]
	v_pk_fma_f32 v[240:241], v[28:29], v[220:221], v[240:241]
	v_pk_fma_f32 v[244:245], v[30:31], v[222:223], v[244:245]
	v_pk_add_f32 v[80:81], v[80:81], v[250:251] op_sel:[0,1] op_sel_hi:[1,1] neg_lo:[0,1] neg_hi:[0,1]
	v_pk_add_f32 v[82:83], v[82:83], v[250:251] op_sel:[0,1] op_sel_hi:[1,1] neg_lo:[0,1] neg_hi:[0,1]
	v_pk_add_f32 v[84:85], v[84:85], v[250:251] op_sel:[0,1] op_sel_hi:[1,1] neg_lo:[0,1] neg_hi:[0,1]
	v_pk_add_f32 v[86:87], v[86:87], v[250:251] op_sel:[0,1] op_sel_hi:[1,1] neg_lo:[0,1] neg_hi:[0,1]
	v_pk_fma_f32 v[80:81], v[192:193], v[80:81], v[250:251] op_sel:[0,0,1] op_sel_hi:[1,1,1]
	v_pk_fma_f32 v[82:83], v[194:195], v[82:83], v[250:251] op_sel:[0,0,1] op_sel_hi:[1,1,1]
	v_pk_fma_f32 v[84:85], v[196:197], v[84:85], v[250:251] op_sel:[0,0,1] op_sel_hi:[1,1,1]
	v_pk_fma_f32 v[86:87], v[198:199], v[86:87], v[250:251] op_sel:[0,0,1] op_sel_hi:[1,1,1]
	v_pk_fma_f32 v[246:247], v[80:81], v[208:209], v[246:247]
	v_pk_fma_f32 v[248:249], v[82:83], v[210:211], v[248:249]
	v_pk_fma_f32 v[246:247], v[84:85], v[212:213], v[246:247]
	v_pk_fma_f32 v[248:249], v[86:87], v[214:215], v[248:249]
	v_pk_add_f32 v[88:89], v[88:89], v[250:251] op_sel:[0,1] op_sel_hi:[1,1] neg_lo:[0,1] neg_hi:[0,1]
	v_pk_add_f32 v[90:91], v[90:91], v[250:251] op_sel:[0,1] op_sel_hi:[1,1] neg_lo:[0,1] neg_hi:[0,1]
	v_pk_add_f32 v[92:93], v[92:93], v[250:251] op_sel:[0,1] op_sel_hi:[1,1] neg_lo:[0,1] neg_hi:[0,1]
	v_pk_add_f32 v[94:95], v[94:95], v[250:251] op_sel:[0,1] op_sel_hi:[1,1] neg_lo:[0,1] neg_hi:[0,1]
	v_pk_fma_f32 v[88:89], v[200:201], v[88:89], v[250:251] op_sel:[0,0,1] op_sel_hi:[1,1,1]
	v_pk_fma_f32 v[90:91], v[202:203], v[90:91], v[250:251] op_sel:[0,0,1] op_sel_hi:[1,1,1]
	v_pk_fma_f32 v[92:93], v[204:205], v[92:93], v[250:251] op_sel:[0,0,1] op_sel_hi:[1,1,1]
	v_pk_fma_f32 v[94:95], v[206:207], v[94:95], v[250:251] op_sel:[0,0,1] op_sel_hi:[1,1,1]
	v_pk_fma_f32 v[246:247], v[88:89], v[216:217], v[246:247]
	v_pk_fma_f32 v[248:249], v[90:91], v[218:219], v[248:249]
	v_pk_fma_f32 v[246:247], v[92:93], v[220:221], v[246:247]
	v_pk_fma_f32 v[248:249], v[94:95], v[222:223], v[248:249]
	ds_read_b128 v[192:195], v135 offset:704
	ds_read_b128 v[196:199], v135 offset:720
	ds_read_b128 v[200:203], v135 offset:736
	ds_read_b128 v[204:207], v135 offset:752
	ds_read_b128 v[208:211], v135 offset:960
	ds_read_b128 v[212:215], v135 offset:976
	ds_read_b128 v[216:219], v135 offset:992
	ds_read_b128 v[220:223], v135 offset:1008
	s_waitcnt lgkmcnt(8)
; __device__ __forceinline__ f2 pfma(f2 a, f2 b, f2 c) { return __builtin_elementwise_fma(a, b, c); }
; __device__ __forceinline__ void hgrn_scan(const bf16_t* __restrict__ PH, int t0, int nsteps, int h, int half, int kh, int lane, float lb, f2 (&S)[32], float& cp, bf16_t* __restrict__ OHp, float* __restrict__ ckp, LAS float* L) {
;     ...
;         for (int g = 0; g < 4; ++g) {
;             if (g < 3) {
; #pragma unroll
;                 for (int i = 0; i < 4; ++i) { F[(g + 1) & 1][i] = pf[(g + 1) * 4 + i]; Q[(g + 1) & 1][i] = pf[16 + (g + 1) * 4 + i]; } }
;             __builtin_amdgcn_sched_barrier(0);
; #pragma unroll
;             for (int i = 0; i < 4; ++i) {
;                 const f32x4 f4 = F[g & 1][i], q4 = Q[g & 1][i]; const int idx = (g * 4 + i) * 2;
;                 const f2 f01 = {f4[0], f4[1]}, f23 = {f4[2], f4[3]}, q01 = {q4[0], q4[1]}, q23 = {q4[2], q4[3]};
;                 S[idx] = pfma(f01, S[idx] - v2, v2); o2 = pfma(S[idx], q01, o2);
;                 S[idx + 1] = pfma(f23, S[idx + 1] - v2, v2); o3 = pfma(S[idx + 1], q23, o3);
;             }
	v_pk_add_f32 v[32:33], v[32:33], v[250:251] op_sel_hi:[1,0] neg_lo:[0,1] neg_hi:[0,1]
	v_pk_add_f32 v[34:35], v[34:35], v[250:251] op_sel_hi:[1,0] neg_lo:[0,1] neg_hi:[0,1]
	v_pk_add_f32 v[36:37], v[36:37], v[250:251] op_sel_hi:[1,0] neg_lo:[0,1] neg_hi:[0,1]
	v_pk_add_f32 v[38:39], v[38:39], v[250:251] op_sel_hi:[1,0] neg_lo:[0,1] neg_hi:[0,1]
	v_pk_fma_f32 v[32:33], v[148:149], v[32:33], v[250:251] op_sel_hi:[1,1,0]
	v_pk_fma_f32 v[34:35], v[150:151], v[34:35], v[250:251] op_sel_hi:[1,1,0]
	v_pk_fma_f32 v[36:37], v[152:153], v[36:37], v[250:251] op_sel_hi:[1,1,0]
	v_pk_fma_f32 v[38:39], v[154:155], v[38:39], v[250:251] op_sel_hi:[1,1,0]
	v_pk_fma_f32 v[240:241], v[32:33], v[164:165], v[240:241]
	v_pk_fma_f32 v[244:245], v[34:35], v[166:167], v[244:245]
	v_pk_fma_f32 v[240:241], v[36:37], v[168:169], v[240:241]
	v_pk_fma_f32 v[244:245], v[38:39], v[170:171], v[244:245]
	v_pk_add_f32 v[40:41], v[40:41], v[250:251] op_sel_hi:[1,0] neg_lo:[0,1] neg_hi:[0,1]
	v_pk_add_f32 v[42:43], v[42:43], v[250:251] op_sel_hi:[1,0] neg_lo:[0,1] neg_hi:[0,1]
	v_pk_add_f32 v[44:45], v[44:45], v[250:251] op_sel_hi:[1,0] neg_lo:[0,1] neg_hi:[0,1]
	v_pk_add_f32 v[46:47], v[46:47], v[250:251] op_sel_hi:[1,0] neg_lo:[0,1] neg_hi:[0,1]
	v_pk_fma_f32 v[40:41], v[156:157], v[40:41], v[250:251] op_sel_hi:[1,1,0]
	v_pk_fma_f32 v[42:43], v[158:159], v[42:43], v[250:251] op_sel_hi:[1,1,0]
	v_pk_fma_f32 v[44:45], v[160:161], v[44:45], v[250:251] op_sel_hi:[1,1,0]
	v_pk_fma_f32 v[46:47], v[162:163], v[46:47], v[250:251] op_sel_hi:[1,1,0]
	v_pk_fma_f32 v[240:241], v[40:41], v[172:173], v[240:241]
	v_pk_fma_f32 v[244:245], v[42:43], v[174:175], v[244:245]
	v_pk_fma_f32 v[240:241], v[44:45], v[176:177], v[240:241]
	v_pk_fma_f32 v[244:245], v[46:47], v[178:179], v[244:245]
	v_pk_add_f32 v[96:97], v[96:97], v[250:251] op_sel:[0,1] op_sel_hi:[1,1] neg_lo:[0,1] neg_hi:[0,1]
	v_pk_add_f32 v[98:99], v[98:99], v[250:251] op_sel:[0,1] op_sel_hi:[1,1] neg_lo:[0,1] neg_hi:[0,1]
	v_pk_add_f32 v[100:101], v[100:101], v[250:251] op_sel:[0,1] op_sel_hi:[1,1] neg_lo:[0,1] neg_hi:[0,1]
	v_pk_add_f32 v[102:103], v[102:103], v[250:251] op_sel:[0,1] op_sel_hi:[1,1] neg_lo:[0,1] neg_hi:[0,1]
	v_pk_fma_f32 v[96:97], v[148:149], v[96:97], v[250:251] op_sel:[0,0,1] op_sel_hi:[1,1,1]
	v_pk_fma_f32 v[98:99], v[150:151], v[98:99], v[250:251] op_sel:[0,0,1] op_sel_hi:[1,1,1]
	v_pk_fma_f32 v[100:101], v[152:153], v[100:101], v[250:251] op_sel:[0,0,1] op_sel_hi:[1,1,1]
	v_pk_fma_f32 v[102:103], v[154:155], v[102:103], v[250:251] op_sel:[0,0,1] op_sel_hi:[1,1,1]
	v_pk_fma_f32 v[246:247], v[96:97], v[164:165], v[246:247]
	v_pk_fma_f32 v[248:249], v[98:99], v[166:167], v[248:249]
	v_pk_fma_f32 v[246:247], v[100:101], v[168:169], v[246:247]
	v_pk_fma_f32 v[248:249], v[102:103], v[170:171], v[248:249]
	v_pk_add_f32 v[104:105], v[104:105], v[250:251] op_sel:[0,1] op_sel_hi:[1,1] neg_lo:[0,1] neg_hi:[0,1]
	v_pk_add_f32 v[106:107], v[106:107], v[250:251] op_sel:[0,1] op_sel_hi:[1,1] neg_lo:[0,1] neg_hi:[0,1]
	v_pk_add_f32 v[108:109], v[108:109], v[250:251] op_sel:[0,1] op_sel_hi:[1,1] neg_lo:[0,1] neg_hi:[0,1]
	v_pk_add_f32 v[110:111], v[110:111], v[250:251] op_sel:[0,1] op_sel_hi:[1,1] neg_lo:[0,1] neg_hi:[0,1]
	v_pk_fma_f32 v[104:105], v[156:157], v[104:105], v[250:251] op_sel:[0,0,1] op_sel_hi:[1,1,1]
	v_pk_fma_f32 v[106:107], v[158:159], v[106:107], v[250:251] op_sel:[0,0,1] op_sel_hi:[1,1,1]
	v_pk_fma_f32 v[108:109], v[160:161], v[108:109], v[250:251] op_sel:[0,0,1] op_sel_hi:[1,1,1]
	v_pk_fma_f32 v[110:111], v[162:163], v[110:111], v[250:251] op_sel:[0,0,1] op_sel_hi:[1,1,1]
	v_pk_fma_f32 v[246:247], v[104:105], v[172:173], v[246:247]
	v_pk_fma_f32 v[248:249], v[106:107], v[174:175], v[248:249]
	v_pk_fma_f32 v[246:247], v[108:109], v[176:177], v[246:247]
	v_pk_fma_f32 v[248:249], v[110:111], v[178:179], v[248:249]
	ds_read_b128 v[148:151], v135 offset:0
	ds_read_b128 v[152:155], v135 offset:16
	ds_read_b128 v[156:159], v135 offset:32
	ds_read_b128 v[160:163], v135 offset:48
	ds_read_b128 v[164:167], v135 offset:256
	ds_read_b128 v[168:171], v135 offset:272
	ds_read_b128 v[172:175], v135 offset:288
	ds_read_b128 v[176:179], v135 offset:304
	s_waitcnt lgkmcnt(8)
	v_pk_add_f32 v[48:49], v[48:49], v[250:251] op_sel_hi:[1,0] neg_lo:[0,1] neg_hi:[0,1]
	v_pk_add_f32 v[50:51], v[50:51], v[250:251] op_sel_hi:[1,0] neg_lo:[0,1] neg_hi:[0,1]
	v_pk_add_f32 v[52:53], v[52:53], v[250:251] op_sel_hi:[1,0] neg_lo:[0,1] neg_hi:[0,1]
	v_pk_add_f32 v[54:55], v[54:55], v[250:251] op_sel_hi:[1,0] neg_lo:[0,1] neg_hi:[0,1]
	v_pk_fma_f32 v[48:49], v[192:193], v[48:49], v[250:251] op_sel_hi:[1,1,0]
	v_pk_fma_f32 v[50:51], v[194:195], v[50:51], v[250:251] op_sel_hi:[1,1,0]
	v_pk_fma_f32 v[52:53], v[196:197], v[52:53], v[250:251] op_sel_hi:[1,1,0]
	v_pk_fma_f32 v[54:55], v[198:199], v[54:55], v[250:251] op_sel_hi:[1,1,0]
	v_pk_fma_f32 v[240:241], v[48:49], v[208:209], v[240:241]
	v_pk_fma_f32 v[244:245], v[50:51], v[210:211], v[244:245]
	v_pk_fma_f32 v[240:241], v[52:53], v[212:213], v[240:241]
	v_pk_fma_f32 v[244:245], v[54:55], v[214:215], v[244:245]
	v_pk_add_f32 v[56:57], v[56:57], v[250:251] op_sel_hi:[1,0] neg_lo:[0,1] neg_hi:[0,1]
	v_pk_add_f32 v[58:59], v[58:59], v[250:251] op_sel_hi:[1,0] neg_lo:[0,1] neg_hi:[0,1]
	v_pk_add_f32 v[60:61], v[60:61], v[250:251] op_sel_hi:[1,0] neg_lo:[0,1] neg_hi:[0,1]
	v_pk_add_f32 v[62:63], v[62:63], v[250:251] op_sel_hi:[1,0] neg_lo:[0,1] neg_hi:[0,1]
	v_pk_fma_f32 v[56:57], v[200:201], v[56:57], v[250:251] op_sel_hi:[1,1,0]
	v_pk_fma_f32 v[58:59], v[202:203], v[58:59], v[250:251] op_sel_hi:[1,1,0]
	v_pk_fma_f32 v[60:61], v[204:205], v[60:61], v[250:251] op_sel_hi:[1,1,0]
; __device__ __forceinline__ float bf2f(unsigned short b) { return __uint_as_float((unsigned)b << 16); }
; __device__ __forceinline__ unsigned short f2bf(float f) { unsigned u = __float_as_uint(f); u += 0x7FFFu + ((u >> 16) & 1u); return (unsigned short)(u >> 16); }
; __device__ __forceinline__ float sigm(float x) { return __builtin_amdgcn_rcpf(1.0f + __expf(-x)); }
; __device__ __forceinline__ f2 pfma(f2 a, f2 b, f2 c) { return __builtin_elementwise_fma(a, b, c); }
; __device__ __forceinline__ void hgrn_scan(const bf16_t* __restrict__ PH, int t0, int nsteps, int h, int half, int kh, int lane, float lb, f2 (&S)[32], float& cp, bf16_t* __restrict__ OHp, float* __restrict__ ckp, LAS float* L) {
;     ...
;     for (int s = 0; s < nsteps; ++s) {
;         const float ql = bf2f(q1[0]), fz = bf2f(q1[1]), v = bf2f(q1[2]);
; #pragma unroll
;         for (int j = 0; j < 3; ++j) { q1[j] = q2[j]; q2[j] = q3[j]; }
;         { const bf16_t* r = row + (size_t)(s + 3 < nsteps ? s + 3 : nsteps - 1) * 2048; q3[0] = r[0]; q3[1] = r[512]; q3[2] = r[voff]; }
;         const float fl = lb + (1.0f - lb) * sigm(fz);
;         cp *= fl;
;         if (ckp && (s & 31) == 31 && s < 127) ckp[(s >> 5) * 128 + lane] = cp;
;         L[lane] = fl; L[64 + lane] = ql * sigm(ql);
;         f32x4 F[2][4], Q[2][4];
; #pragma unroll
;         for (int i = 0; i < 4; ++i) { F[0][i] = pf[i]; Q[0][i] = pf[16 + i]; }
;         const f2 v2 = {v, v}; f2 o2 = {0.f, 0.f}, o3 = {0.f, 0.f};
; #pragma unroll
;         for (int g = 0; g < 4; ++g) {
;             if (g < 3) {
; #pragma unroll
;                 for (int i = 0; i < 4; ++i) { F[(g + 1) & 1][i] = pf[(g + 1) * 4 + i]; Q[(g + 1) & 1][i] = pf[16 + (g + 1) * 4 + i]; } }
;             __builtin_amdgcn_sched_barrier(0);
; #pragma unroll
;             for (int i = 0; i < 4; ++i) {
;                 const f32x4 f4 = F[g & 1][i], q4 = Q[g & 1][i]; const int idx = (g * 4 + i) * 2;
;                 const f2 f01 = {f4[0], f4[1]}, f23 = {f4[2], f4[3]}, q01 = {q4[0], q4[1]}, q23 = {q4[2], q4[3]};
;                 S[idx] = pfma(f01, S[idx] - v2, v2); o2 = pfma(S[idx], q01, o2);
;                 S[idx + 1] = pfma(f23, S[idx + 1] - v2, v2); o3 = pfma(S[idx + 1], q23, o3);
;             }
;         }
;         OHp[(size_t)(t0 + s) * 512 + h * 128 + half * 64 + lane] = f2bf((o2[0] + o2[1]) + (o3[0] + o3[1]));
	v_pk_fma_f32 v[62:63], v[206:207], v[62:63], v[250:251] op_sel_hi:[1,1,0]
	v_pk_fma_f32 v[240:241], v[56:57], v[216:217], v[240:241]
	v_pk_fma_f32 v[244:245], v[58:59], v[218:219], v[244:245]
	v_pk_fma_f32 v[240:241], v[60:61], v[220:221], v[240:241]
	v_pk_fma_f32 v[244:245], v[62:63], v[222:223], v[244:245]
	v_pk_add_f32 v[112:113], v[112:113], v[250:251] op_sel:[0,1] op_sel_hi:[1,1] neg_lo:[0,1] neg_hi:[0,1]
	v_pk_add_f32 v[114:115], v[114:115], v[250:251] op_sel:[0,1] op_sel_hi:[1,1] neg_lo:[0,1] neg_hi:[0,1]
	v_pk_add_f32 v[116:117], v[116:117], v[250:251] op_sel:[0,1] op_sel_hi:[1,1] neg_lo:[0,1] neg_hi:[0,1]
	v_pk_add_f32 v[118:119], v[118:119], v[250:251] op_sel:[0,1] op_sel_hi:[1,1] neg_lo:[0,1] neg_hi:[0,1]
	v_pk_fma_f32 v[112:113], v[192:193], v[112:113], v[250:251] op_sel:[0,0,1] op_sel_hi:[1,1,1]
	v_pk_fma_f32 v[114:115], v[194:195], v[114:115], v[250:251] op_sel:[0,0,1] op_sel_hi:[1,1,1]
	v_pk_fma_f32 v[116:117], v[196:197], v[116:117], v[250:251] op_sel:[0,0,1] op_sel_hi:[1,1,1]
	v_pk_fma_f32 v[118:119], v[198:199], v[118:119], v[250:251] op_sel:[0,0,1] op_sel_hi:[1,1,1]
	v_pk_fma_f32 v[246:247], v[112:113], v[208:209], v[246:247]
	v_pk_fma_f32 v[248:249], v[114:115], v[210:211], v[248:249]
	v_pk_fma_f32 v[246:247], v[116:117], v[212:213], v[246:247]
	v_pk_fma_f32 v[248:249], v[118:119], v[214:215], v[248:249]
	v_pk_add_f32 v[120:121], v[120:121], v[250:251] op_sel:[0,1] op_sel_hi:[1,1] neg_lo:[0,1] neg_hi:[0,1]
	v_pk_add_f32 v[122:123], v[122:123], v[250:251] op_sel:[0,1] op_sel_hi:[1,1] neg_lo:[0,1] neg_hi:[0,1]
	v_pk_add_f32 v[124:125], v[124:125], v[250:251] op_sel:[0,1] op_sel_hi:[1,1] neg_lo:[0,1] neg_hi:[0,1]
	v_pk_add_f32 v[126:127], v[126:127], v[250:251] op_sel:[0,1] op_sel_hi:[1,1] neg_lo:[0,1] neg_hi:[0,1]
	v_pk_fma_f32 v[120:121], v[200:201], v[120:121], v[250:251] op_sel:[0,0,1] op_sel_hi:[1,1,1]
	v_pk_fma_f32 v[122:123], v[202:203], v[122:123], v[250:251] op_sel:[0,0,1] op_sel_hi:[1,1,1]
	v_pk_fma_f32 v[124:125], v[204:205], v[124:125], v[250:251] op_sel:[0,0,1] op_sel_hi:[1,1,1]
	v_pk_fma_f32 v[126:127], v[206:207], v[126:127], v[250:251] op_sel:[0,0,1] op_sel_hi:[1,1,1]
	v_pk_fma_f32 v[246:247], v[120:121], v[216:217], v[246:247]
	v_pk_fma_f32 v[248:249], v[122:123], v[218:219], v[248:249]
	v_pk_fma_f32 v[246:247], v[124:125], v[220:221], v[246:247]
	v_pk_fma_f32 v[248:249], v[126:127], v[222:223], v[248:249]
	v_add_f32_e32 v240, v240, v241
	v_add_f32_e32 v244, v244, v245
	v_add_f32_e32 v240, v240, v244
	v_bfe_u32 v244, v240, 16, 1
	v_add3_u32 v240, v240, v244, s69
	global_store_short_d16_hi v138, v240, s[26:27]
	v_add_f32_e32 v246, v246, v247
	v_add_f32_e32 v248, v248, v249
	v_add_f32_e32 v246, v246, v248
	v_bfe_u32 v248, v246, 16, 1
	v_add3_u32 v246, v246, v248, s69
	global_store_short_d16_hi v138, v246, s[26:27] offset:128
	v_mov_b32_e32 v250, v252
	v_mov_b32_e32 v251, v253
	v_add_u32_e32 v138, 0x400, v138
	global_load_ushort v232, v136, s[24:25]
	global_load_ushort v233, v136, s[24:25] offset:1024
	global_load_ushort v234, v137, s[24:25]
	global_load_ushort v235, v137, s[24:25] offset:128
	v_add_u32_e32 v136, 0x1000, v136
	v_add_u32_e32 v137, 0x1000, v137
	ds_read_b128 v[192:195], v135 offset:64
	ds_read_b128 v[196:199], v135 offset:80
	ds_read_b128 v[200:203], v135 offset:96
	ds_read_b128 v[204:207], v135 offset:112
	ds_read_b128 v[208:211], v135 offset:320
	ds_read_b128 v[212:215], v135 offset:336
	ds_read_b128 v[216:219], v135 offset:352
	ds_read_b128 v[220:223], v135 offset:368
	s_waitcnt lgkmcnt(8)
	v_pk_add_f32 v[0:1], v[0:1], v[250:251] op_sel_hi:[1,0] neg_lo:[0,1] neg_hi:[0,1]
	v_pk_add_f32 v[2:3], v[2:3], v[250:251] op_sel_hi:[1,0] neg_lo:[0,1] neg_hi:[0,1]
	v_pk_add_f32 v[4:5], v[4:5], v[250:251] op_sel_hi:[1,0] neg_lo:[0,1] neg_hi:[0,1]
	v_pk_add_f32 v[6:7], v[6:7], v[250:251] op_sel_hi:[1,0] neg_lo:[0,1] neg_hi:[0,1]
	v_pk_fma_f32 v[0:1], v[148:149], v[0:1], v[250:251] op_sel_hi:[1,1,0]
	v_pk_fma_f32 v[2:3], v[150:151], v[2:3], v[250:251] op_sel_hi:[1,1,0]
	v_pk_fma_f32 v[4:5], v[152:153], v[4:5], v[250:251] op_sel_hi:[1,1,0]
	v_pk_fma_f32 v[6:7], v[154:155], v[6:7], v[250:251] op_sel_hi:[1,1,0]
	v_pk_fma_f32 v[240:241], v[0:1], v[164:165], 0 op_sel_hi:[1,1,0]
	v_pk_fma_f32 v[244:245], v[2:3], v[166:167], 0 op_sel_hi:[1,1,0]
	v_pk_fma_f32 v[240:241], v[4:5], v[168:169], v[240:241]
	v_pk_fma_f32 v[244:245], v[6:7], v[170:171], v[244:245]
	v_pk_add_f32 v[8:9], v[8:9], v[250:251] op_sel_hi:[1,0] neg_lo:[0,1] neg_hi:[0,1]
	v_pk_add_f32 v[10:11], v[10:11], v[250:251] op_sel_hi:[1,0] neg_lo:[0,1] neg_hi:[0,1]
	v_pk_add_f32 v[12:13], v[12:13], v[250:251] op_sel_hi:[1,0] neg_lo:[0,1] neg_hi:[0,1]
	v_pk_add_f32 v[14:15], v[14:15], v[250:251] op_sel_hi:[1,0] neg_lo:[0,1] neg_hi:[0,1]
	v_pk_fma_f32 v[8:9], v[156:157], v[8:9], v[250:251] op_sel_hi:[1,1,0]
	v_pk_fma_f32 v[10:11], v[158:159], v[10:11], v[250:251] op_sel_hi:[1,1,0]
	v_pk_fma_f32 v[12:13], v[160:161], v[12:13], v[250:251] op_sel_hi:[1,1,0]
	v_pk_fma_f32 v[14:15], v[162:163], v[14:15], v[250:251] op_sel_hi:[1,1,0]
	v_pk_fma_f32 v[240:241], v[8:9], v[172:173], v[240:241]
	v_pk_fma_f32 v[244:245], v[10:11], v[174:175], v[244:245]
	v_pk_fma_f32 v[240:241], v[12:13], v[176:177], v[240:241]
	v_pk_fma_f32 v[244:245], v[14:15], v[178:179], v[244:245]
	v_pk_add_f32 v[64:65], v[64:65], v[250:251] op_sel:[0,1] op_sel_hi:[1,1] neg_lo:[0,1] neg_hi:[0,1]
	v_pk_add_f32 v[66:67], v[66:67], v[250:251] op_sel:[0,1] op_sel_hi:[1,1] neg_lo:[0,1] neg_hi:[0,1]
	v_pk_add_f32 v[68:69], v[68:69], v[250:251] op_sel:[0,1] op_sel_hi:[1,1] neg_lo:[0,1] neg_hi:[0,1]
	v_pk_add_f32 v[70:71], v[70:71], v[250:251] op_sel:[0,1] op_sel_hi:[1,1] neg_lo:[0,1] neg_hi:[0,1]
; __device__ __forceinline__ float bf2f(unsigned short b) { return __uint_as_float((unsigned)b << 16); }
; __device__ __forceinline__ float sigm(float x) { return __builtin_amdgcn_rcpf(1.0f + __expf(-x)); }
; __device__ __forceinline__ f2 pfma(f2 a, f2 b, f2 c) { return __builtin_elementwise_fma(a, b, c); }
; __device__ __forceinline__ void hgrn_scan(const bf16_t* __restrict__ PH, int t0, int nsteps, int h, int half, int kh, int lane, float lb, f2 (&S)[32], float& cp, bf16_t* __restrict__ OHp, float* __restrict__ ckp, LAS float* L) {
;     ...
;     for (int s = 0; s < nsteps; ++s) {
;         const float ql = bf2f(q1[0]), fz = bf2f(q1[1]), v = bf2f(q1[2]);
; #pragma unroll
;         for (int j = 0; j < 3; ++j) { q1[j] = q2[j]; q2[j] = q3[j]; }
;         { const bf16_t* r = row + (size_t)(s + 3 < nsteps ? s + 3 : nsteps - 1) * 2048; q3[0] = r[0]; q3[1] = r[512]; q3[2] = r[voff]; }
;         const float fl = lb + (1.0f - lb) * sigm(fz);
;         cp *= fl;
;         if (ckp && (s & 31) == 31 && s < 127) ckp[(s >> 5) * 128 + lane] = cp;
;         L[lane] = fl; L[64 + lane] = ql * sigm(ql);
;         f32x4 F[2][4], Q[2][4];
; #pragma unroll
;         for (int i = 0; i < 4; ++i) { F[0][i] = pf[i]; Q[0][i] = pf[16 + i]; }
;         const f2 v2 = {v, v}; f2 o2 = {0.f, 0.f}, o3 = {0.f, 0.f};
; #pragma unroll
;         for (int g = 0; g < 4; ++g) {
;             if (g < 3) {
; #pragma unroll
;                 for (int i = 0; i < 4; ++i) { F[(g + 1) & 1][i] = pf[(g + 1) * 4 + i]; Q[(g + 1) & 1][i] = pf[16 + (g + 1) * 4 + i]; } }
;             __builtin_amdgcn_sched_barrier(0);
; #pragma unroll
;             for (int i = 0; i < 4; ++i) {
;                 const f32x4 f4 = F[g & 1][i], q4 = Q[g & 1][i]; const int idx = (g * 4 + i) * 2;
;                 const f2 f01 = {f4[0], f4[1]}, f23 = {f4[2], f4[3]}, q01 = {q4[0], q4[1]}, q23 = {q4[2], q4[3]};
;                 S[idx] = pfma(f01, S[idx] - v2, v2); o2 = pfma(S[idx], q01, o2);
;                 S[idx + 1] = pfma(f23, S[idx + 1] - v2, v2); o3 = pfma(S[idx + 1], q23, o3);
;             }
	v_pk_fma_f32 v[64:65], v[148:149], v[64:65], v[250:251] op_sel:[0,0,1] op_sel_hi:[1,1,1]
	v_pk_fma_f32 v[66:67], v[150:151], v[66:67], v[250:251] op_sel:[0,0,1] op_sel_hi:[1,1,1]
	v_pk_fma_f32 v[68:69], v[152:153], v[68:69], v[250:251] op_sel:[0,0,1] op_sel_hi:[1,1,1]
	v_pk_fma_f32 v[70:71], v[154:155], v[70:71], v[250:251] op_sel:[0,0,1] op_sel_hi:[1,1,1]
	v_pk_fma_f32 v[246:247], v[64:65], v[164:165], 0 op_sel_hi:[1,1,0]
	v_pk_fma_f32 v[248:249], v[66:67], v[166:167], 0 op_sel_hi:[1,1,0]
	v_pk_fma_f32 v[246:247], v[68:69], v[168:169], v[246:247]
	v_pk_fma_f32 v[248:249], v[70:71], v[170:171], v[248:249]
	v_pk_add_f32 v[72:73], v[72:73], v[250:251] op_sel:[0,1] op_sel_hi:[1,1] neg_lo:[0,1] neg_hi:[0,1]
	v_pk_add_f32 v[74:75], v[74:75], v[250:251] op_sel:[0,1] op_sel_hi:[1,1] neg_lo:[0,1] neg_hi:[0,1]
	v_pk_add_f32 v[76:77], v[76:77], v[250:251] op_sel:[0,1] op_sel_hi:[1,1] neg_lo:[0,1] neg_hi:[0,1]
	v_pk_add_f32 v[78:79], v[78:79], v[250:251] op_sel:[0,1] op_sel_hi:[1,1] neg_lo:[0,1] neg_hi:[0,1]
	v_pk_fma_f32 v[72:73], v[156:157], v[72:73], v[250:251] op_sel:[0,0,1] op_sel_hi:[1,1,1]
	v_pk_fma_f32 v[74:75], v[158:159], v[74:75], v[250:251] op_sel:[0,0,1] op_sel_hi:[1,1,1]
	v_pk_fma_f32 v[76:77], v[160:161], v[76:77], v[250:251] op_sel:[0,0,1] op_sel_hi:[1,1,1]
	v_pk_fma_f32 v[78:79], v[162:163], v[78:79], v[250:251] op_sel:[0,0,1] op_sel_hi:[1,1,1]
	v_pk_fma_f32 v[246:247], v[72:73], v[172:173], v[246:247]
	v_pk_fma_f32 v[248:249], v[74:75], v[174:175], v[248:249]
	v_pk_fma_f32 v[246:247], v[76:77], v[176:177], v[246:247]
	v_pk_fma_f32 v[248:249], v[78:79], v[178:179], v[248:249]
	s_waitcnt vmcnt(16)
	v_lshlrev_b32_e32 v140, 16, v237
	v_lshlrev_b32_e32 v141, 16, v236
	v_mul_f32_e32 v142, 0xbfb8aa3b, v140
	v_mul_f32_e32 v143, 0xbfb8aa3b, v141
	v_exp_f32_e32 v142, v142
	v_exp_f32_e32 v143, v143
	v_lshlrev_b32_e32 v252, 16, v238
	v_lshlrev_b32_e32 v253, 16, v239
	v_add_f32_e32 v142, 1.0, v142
	v_add_f32_e32 v143, 1.0, v143
	v_rcp_f32_e32 v142, v142
	v_rcp_f32_e32 v143, v143
	v_fma_f32 v142, v131, v142, v130
	v_mul_f32_e32 v143, v143, v141
	v_mul_f32_e32 v132, v132, v142
	ds_write2st64_b32 v134, v142, v143 offset0:2 offset1:3
	ds_read_b128 v[148:151], v135 offset:128
	ds_read_b128 v[152:155], v135 offset:144
	ds_read_b128 v[156:159], v135 offset:160
	ds_read_b128 v[160:163], v135 offset:176
	ds_read_b128 v[164:167], v135 offset:384
	ds_read_b128 v[168:171], v135 offset:400
	ds_read_b128 v[172:175], v135 offset:416
	ds_read_b128 v[176:179], v135 offset:432
	s_waitcnt lgkmcnt(9)
	v_pk_add_f32 v[16:17], v[16:17], v[250:251] op_sel_hi:[1,0] neg_lo:[0,1] neg_hi:[0,1]
	v_pk_add_f32 v[18:19], v[18:19], v[250:251] op_sel_hi:[1,0] neg_lo:[0,1] neg_hi:[0,1]
	v_pk_add_f32 v[20:21], v[20:21], v[250:251] op_sel_hi:[1,0] neg_lo:[0,1] neg_hi:[0,1]
	v_pk_add_f32 v[22:23], v[22:23], v[250:251] op_sel_hi:[1,0] neg_lo:[0,1] neg_hi:[0,1]
	v_pk_fma_f32 v[16:17], v[192:193], v[16:17], v[250:251] op_sel_hi:[1,1,0]
	v_pk_fma_f32 v[18:19], v[194:195], v[18:19], v[250:251] op_sel_hi:[1,1,0]
	v_pk_fma_f32 v[20:21], v[196:197], v[20:21], v[250:251] op_sel_hi:[1,1,0]
	v_pk_fma_f32 v[22:23], v[198:199], v[22:23], v[250:251] op_sel_hi:[1,1,0]
	v_pk_fma_f32 v[240:241], v[16:17], v[208:209], v[240:241]
	v_pk_fma_f32 v[244:245], v[18:19], v[210:211], v[244:245]
	v_pk_fma_f32 v[240:241], v[20:21], v[212:213], v[240:241]
	v_pk_fma_f32 v[244:245], v[22:23], v[214:215], v[244:245]
	v_pk_add_f32 v[24:25], v[24:25], v[250:251] op_sel_hi:[1,0] neg_lo:[0,1] neg_hi:[0,1]
	v_pk_add_f32 v[26:27], v[26:27], v[250:251] op_sel_hi:[1,0] neg_lo:[0,1] neg_hi:[0,1]
	v_pk_add_f32 v[28:29], v[28:29], v[250:251] op_sel_hi:[1,0] neg_lo:[0,1] neg_hi:[0,1]
	v_pk_add_f32 v[30:31], v[30:31], v[250:251] op_sel_hi:[1,0] neg_lo:[0,1] neg_hi:[0,1]
	v_pk_fma_f32 v[24:25], v[200:201], v[24:25], v[250:251] op_sel_hi:[1,1,0]
	v_pk_fma_f32 v[26:27], v[202:203], v[26:27], v[250:251] op_sel_hi:[1,1,0]
	v_pk_fma_f32 v[28:29], v[204:205], v[28:29], v[250:251] op_sel_hi:[1,1,0]
	v_pk_fma_f32 v[30:31], v[206:207], v[30:31], v[250:251] op_sel_hi:[1,1,0]
	v_pk_fma_f32 v[240:241], v[24:25], v[216:217], v[240:241]
	v_pk_fma_f32 v[244:245], v[26:27], v[218:219], v[244:245]
	v_pk_fma_f32 v[240:241], v[28:29], v[220:221], v[240:241]
	v_pk_fma_f32 v[244:245], v[30:31], v[222:223], v[244:245]
	v_pk_add_f32 v[80:81], v[80:81], v[250:251] op_sel:[0,1] op_sel_hi:[1,1] neg_lo:[0,1] neg_hi:[0,1]
	v_pk_add_f32 v[82:83], v[82:83], v[250:251] op_sel:[0,1] op_sel_hi:[1,1] neg_lo:[0,1] neg_hi:[0,1]
	v_pk_add_f32 v[84:85], v[84:85], v[250:251] op_sel:[0,1] op_sel_hi:[1,1] neg_lo:[0,1] neg_hi:[0,1]
	v_pk_add_f32 v[86:87], v[86:87], v[250:251] op_sel:[0,1] op_sel_hi:[1,1] neg_lo:[0,1] neg_hi:[0,1]
	v_pk_fma_f32 v[80:81], v[192:193], v[80:81], v[250:251] op_sel:[0,0,1] op_sel_hi:[1,1,1]
	v_pk_fma_f32 v[82:83], v[194:195], v[82:83], v[250:251] op_sel:[0,0,1] op_sel_hi:[1,1,1]
	v_pk_fma_f32 v[84:85], v[196:197], v[84:85], v[250:251] op_sel:[0,0,1] op_sel_hi:[1,1,1]
	v_pk_fma_f32 v[86:87], v[198:199], v[86:87], v[250:251] op_sel:[0,0,1] op_sel_hi:[1,1,1]
	v_pk_fma_f32 v[246:247], v[80:81], v[208:209], v[246:247]
	v_pk_fma_f32 v[248:249], v[82:83], v[210:211], v[248:249]
	v_pk_fma_f32 v[246:247], v[84:85], v[212:213], v[246:247]
	v_pk_fma_f32 v[248:249], v[86:87], v[214:215], v[248:249]
	v_pk_add_f32 v[88:89], v[88:89], v[250:251] op_sel:[0,1] op_sel_hi:[1,1] neg_lo:[0,1] neg_hi:[0,1]
	v_pk_add_f32 v[90:91], v[90:91], v[250:251] op_sel:[0,1] op_sel_hi:[1,1] neg_lo:[0,1] neg_hi:[0,1]
	v_pk_add_f32 v[92:93], v[92:93], v[250:251] op_sel:[0,1] op_sel_hi:[1,1] neg_lo:[0,1] neg_hi:[0,1]
	v_pk_add_f32 v[94:95], v[94:95], v[250:251] op_sel:[0,1] op_sel_hi:[1,1] neg_lo:[0,1] neg_hi:[0,1]
	v_pk_fma_f32 v[88:89], v[200:201], v[88:89], v[250:251] op_sel:[0,0,1] op_sel_hi:[1,1,1]
	v_pk_fma_f32 v[90:91], v[202:203], v[90:91], v[250:251] op_sel:[0,0,1] op_sel_hi:[1,1,1]
	v_pk_fma_f32 v[92:93], v[204:205], v[92:93], v[250:251] op_sel:[0,0,1] op_sel_hi:[1,1,1]
	v_pk_fma_f32 v[94:95], v[206:207], v[94:95], v[250:251] op_sel:[0,0,1] op_sel_hi:[1,1,1]
	v_pk_fma_f32 v[246:247], v[88:89], v[216:217], v[246:247]
	v_pk_fma_f32 v[248:249], v[90:91], v[218:219], v[248:249]
	v_pk_fma_f32 v[246:247], v[92:93], v[220:221], v[246:247]
	v_pk_fma_f32 v[248:249], v[94:95], v[222:223], v[248:249]
	ds_read_b128 v[192:195], v135 offset:192
	ds_read_b128 v[196:199], v135 offset:208
	ds_read_b128 v[200:203], v135 offset:224
	ds_read_b128 v[204:207], v135 offset:240
	ds_read_b128 v[208:211], v135 offset:448
	ds_read_b128 v[212:215], v135 offset:464
	ds_read_b128 v[216:219], v135 offset:480
	ds_read_b128 v[220:223], v135 offset:496
	s_waitcnt lgkmcnt(8)
; __device__ __forceinline__ f2 pfma(f2 a, f2 b, f2 c) { return __builtin_elementwise_fma(a, b, c); }
; __device__ __forceinline__ void hgrn_scan(const bf16_t* __restrict__ PH, int t0, int nsteps, int h, int half, int kh, int lane, float lb, f2 (&S)[32], float& cp, bf16_t* __restrict__ OHp, float* __restrict__ ckp, LAS float* L) {
;     ...
;         for (int g = 0; g < 4; ++g) {
;             if (g < 3) {
; #pragma unroll
;                 for (int i = 0; i < 4; ++i) { F[(g + 1) & 1][i] = pf[(g + 1) * 4 + i]; Q[(g + 1) & 1][i] = pf[16 + (g + 1) * 4 + i]; } }
;             __builtin_amdgcn_sched_barrier(0);
; #pragma unroll
;             for (int i = 0; i < 4; ++i) {
;                 const f32x4 f4 = F[g & 1][i], q4 = Q[g & 1][i]; const int idx = (g * 4 + i) * 2;
;                 const f2 f01 = {f4[0], f4[1]}, f23 = {f4[2], f4[3]}, q01 = {q4[0], q4[1]}, q23 = {q4[2], q4[3]};
;                 S[idx] = pfma(f01, S[idx] - v2, v2); o2 = pfma(S[idx], q01, o2);
;                 S[idx + 1] = pfma(f23, S[idx + 1] - v2, v2); o3 = pfma(S[idx + 1], q23, o3);
;             }
	v_pk_add_f32 v[32:33], v[32:33], v[250:251] op_sel_hi:[1,0] neg_lo:[0,1] neg_hi:[0,1]
	v_pk_add_f32 v[34:35], v[34:35], v[250:251] op_sel_hi:[1,0] neg_lo:[0,1] neg_hi:[0,1]
	v_pk_add_f32 v[36:37], v[36:37], v[250:251] op_sel_hi:[1,0] neg_lo:[0,1] neg_hi:[0,1]
	v_pk_add_f32 v[38:39], v[38:39], v[250:251] op_sel_hi:[1,0] neg_lo:[0,1] neg_hi:[0,1]
	v_pk_fma_f32 v[32:33], v[148:149], v[32:33], v[250:251] op_sel_hi:[1,1,0]
	v_pk_fma_f32 v[34:35], v[150:151], v[34:35], v[250:251] op_sel_hi:[1,1,0]
	v_pk_fma_f32 v[36:37], v[152:153], v[36:37], v[250:251] op_sel_hi:[1,1,0]
	v_pk_fma_f32 v[38:39], v[154:155], v[38:39], v[250:251] op_sel_hi:[1,1,0]
	v_pk_fma_f32 v[240:241], v[32:33], v[164:165], v[240:241]
	v_pk_fma_f32 v[244:245], v[34:35], v[166:167], v[244:245]
	v_pk_fma_f32 v[240:241], v[36:37], v[168:169], v[240:241]
	v_pk_fma_f32 v[244:245], v[38:39], v[170:171], v[244:245]
	v_pk_add_f32 v[40:41], v[40:41], v[250:251] op_sel_hi:[1,0] neg_lo:[0,1] neg_hi:[0,1]
	v_pk_add_f32 v[42:43], v[42:43], v[250:251] op_sel_hi:[1,0] neg_lo:[0,1] neg_hi:[0,1]
	v_pk_add_f32 v[44:45], v[44:45], v[250:251] op_sel_hi:[1,0] neg_lo:[0,1] neg_hi:[0,1]
	v_pk_add_f32 v[46:47], v[46:47], v[250:251] op_sel_hi:[1,0] neg_lo:[0,1] neg_hi:[0,1]
	v_pk_fma_f32 v[40:41], v[156:157], v[40:41], v[250:251] op_sel_hi:[1,1,0]
	v_pk_fma_f32 v[42:43], v[158:159], v[42:43], v[250:251] op_sel_hi:[1,1,0]
	v_pk_fma_f32 v[44:45], v[160:161], v[44:45], v[250:251] op_sel_hi:[1,1,0]
	v_pk_fma_f32 v[46:47], v[162:163], v[46:47], v[250:251] op_sel_hi:[1,1,0]
	v_pk_fma_f32 v[240:241], v[40:41], v[172:173], v[240:241]
	v_pk_fma_f32 v[244:245], v[42:43], v[174:175], v[244:245]
	v_pk_fma_f32 v[240:241], v[44:45], v[176:177], v[240:241]
	v_pk_fma_f32 v[244:245], v[46:47], v[178:179], v[244:245]
	v_pk_add_f32 v[96:97], v[96:97], v[250:251] op_sel:[0,1] op_sel_hi:[1,1] neg_lo:[0,1] neg_hi:[0,1]
	v_pk_add_f32 v[98:99], v[98:99], v[250:251] op_sel:[0,1] op_sel_hi:[1,1] neg_lo:[0,1] neg_hi:[0,1]
	v_pk_add_f32 v[100:101], v[100:101], v[250:251] op_sel:[0,1] op_sel_hi:[1,1] neg_lo:[0,1] neg_hi:[0,1]
	v_pk_add_f32 v[102:103], v[102:103], v[250:251] op_sel:[0,1] op_sel_hi:[1,1] neg_lo:[0,1] neg_hi:[0,1]
	v_pk_fma_f32 v[96:97], v[148:149], v[96:97], v[250:251] op_sel:[0,0,1] op_sel_hi:[1,1,1]
	v_pk_fma_f32 v[98:99], v[150:151], v[98:99], v[250:251] op_sel:[0,0,1] op_sel_hi:[1,1,1]
	v_pk_fma_f32 v[100:101], v[152:153], v[100:101], v[250:251] op_sel:[0,0,1] op_sel_hi:[1,1,1]
	v_pk_fma_f32 v[102:103], v[154:155], v[102:103], v[250:251] op_sel:[0,0,1] op_sel_hi:[1,1,1]
	v_pk_fma_f32 v[246:247], v[96:97], v[164:165], v[246:247]
	v_pk_fma_f32 v[248:249], v[98:99], v[166:167], v[248:249]
	v_pk_fma_f32 v[246:247], v[100:101], v[168:169], v[246:247]
	v_pk_fma_f32 v[248:249], v[102:103], v[170:171], v[248:249]
	v_pk_add_f32 v[104:105], v[104:105], v[250:251] op_sel:[0,1] op_sel_hi:[1,1] neg_lo:[0,1] neg_hi:[0,1]
	v_pk_add_f32 v[106:107], v[106:107], v[250:251] op_sel:[0,1] op_sel_hi:[1,1] neg_lo:[0,1] neg_hi:[0,1]
	v_pk_add_f32 v[108:109], v[108:109], v[250:251] op_sel:[0,1] op_sel_hi:[1,1] neg_lo:[0,1] neg_hi:[0,1]
	v_pk_add_f32 v[110:111], v[110:111], v[250:251] op_sel:[0,1] op_sel_hi:[1,1] neg_lo:[0,1] neg_hi:[0,1]
	v_pk_fma_f32 v[104:105], v[156:157], v[104:105], v[250:251] op_sel:[0,0,1] op_sel_hi:[1,1,1]
	v_pk_fma_f32 v[106:107], v[158:159], v[106:107], v[250:251] op_sel:[0,0,1] op_sel_hi:[1,1,1]
	v_pk_fma_f32 v[108:109], v[160:161], v[108:109], v[250:251] op_sel:[0,0,1] op_sel_hi:[1,1,1]
	v_pk_fma_f32 v[110:111], v[162:163], v[110:111], v[250:251] op_sel:[0,0,1] op_sel_hi:[1,1,1]
	v_pk_fma_f32 v[246:247], v[104:105], v[172:173], v[246:247]
	v_pk_fma_f32 v[248:249], v[106:107], v[174:175], v[248:249]
	v_pk_fma_f32 v[246:247], v[108:109], v[176:177], v[246:247]
	v_pk_fma_f32 v[248:249], v[110:111], v[178:179], v[248:249]
	ds_read_b128 v[148:151], v135 offset:512
	ds_read_b128 v[152:155], v135 offset:528
	ds_read_b128 v[156:159], v135 offset:544
	ds_read_b128 v[160:163], v135 offset:560
	ds_read_b128 v[164:167], v135 offset:768
	ds_read_b128 v[168:171], v135 offset:784
	ds_read_b128 v[172:175], v135 offset:800
	ds_read_b128 v[176:179], v135 offset:816
	s_waitcnt lgkmcnt(8)
	v_pk_add_f32 v[48:49], v[48:49], v[250:251] op_sel_hi:[1,0] neg_lo:[0,1] neg_hi:[0,1]
	v_pk_add_f32 v[50:51], v[50:51], v[250:251] op_sel_hi:[1,0] neg_lo:[0,1] neg_hi:[0,1]
	v_pk_add_f32 v[52:53], v[52:53], v[250:251] op_sel_hi:[1,0] neg_lo:[0,1] neg_hi:[0,1]
	v_pk_add_f32 v[54:55], v[54:55], v[250:251] op_sel_hi:[1,0] neg_lo:[0,1] neg_hi:[0,1]
	v_pk_fma_f32 v[48:49], v[192:193], v[48:49], v[250:251] op_sel_hi:[1,1,0]
	v_pk_fma_f32 v[50:51], v[194:195], v[50:51], v[250:251] op_sel_hi:[1,1,0]
	v_pk_fma_f32 v[52:53], v[196:197], v[52:53], v[250:251] op_sel_hi:[1,1,0]
	v_pk_fma_f32 v[54:55], v[198:199], v[54:55], v[250:251] op_sel_hi:[1,1,0]
	v_pk_fma_f32 v[240:241], v[48:49], v[208:209], v[240:241]
	v_pk_fma_f32 v[244:245], v[50:51], v[210:211], v[244:245]
	v_pk_fma_f32 v[240:241], v[52:53], v[212:213], v[240:241]
	v_pk_fma_f32 v[244:245], v[54:55], v[214:215], v[244:245]
	v_pk_add_f32 v[56:57], v[56:57], v[250:251] op_sel_hi:[1,0] neg_lo:[0,1] neg_hi:[0,1]
	v_pk_add_f32 v[58:59], v[58:59], v[250:251] op_sel_hi:[1,0] neg_lo:[0,1] neg_hi:[0,1]
	v_pk_add_f32 v[60:61], v[60:61], v[250:251] op_sel_hi:[1,0] neg_lo:[0,1] neg_hi:[0,1]
	v_pk_add_f32 v[62:63], v[62:63], v[250:251] op_sel_hi:[1,0] neg_lo:[0,1] neg_hi:[0,1]
	v_pk_fma_f32 v[56:57], v[200:201], v[56:57], v[250:251] op_sel_hi:[1,1,0]
	v_pk_fma_f32 v[58:59], v[202:203], v[58:59], v[250:251] op_sel_hi:[1,1,0]
	v_pk_fma_f32 v[60:61], v[204:205], v[60:61], v[250:251] op_sel_hi:[1,1,0]
; __device__ __forceinline__ float bf2f(unsigned short b) { return __uint_as_float((unsigned)b << 16); }
; __device__ __forceinline__ unsigned short f2bf(float f) { unsigned u = __float_as_uint(f); u += 0x7FFFu + ((u >> 16) & 1u); return (unsigned short)(u >> 16); }
; __device__ __forceinline__ float sigm(float x) { return __builtin_amdgcn_rcpf(1.0f + __expf(-x)); }
; __device__ __forceinline__ f2 pfma(f2 a, f2 b, f2 c) { return __builtin_elementwise_fma(a, b, c); }
; __device__ __forceinline__ void hgrn_scan(const bf16_t* __restrict__ PH, int t0, int nsteps, int h, int half, int kh, int lane, float lb, f2 (&S)[32], float& cp, bf16_t* __restrict__ OHp, float* __restrict__ ckp, LAS float* L) {
;     ...
;     for (int s = 0; s < nsteps; ++s) {
;         const float ql = bf2f(q1[0]), fz = bf2f(q1[1]), v = bf2f(q1[2]);
; #pragma unroll
;         for (int j = 0; j < 3; ++j) { q1[j] = q2[j]; q2[j] = q3[j]; }
;         { const bf16_t* r = row + (size_t)(s + 3 < nsteps ? s + 3 : nsteps - 1) * 2048; q3[0] = r[0]; q3[1] = r[512]; q3[2] = r[voff]; }
;         const float fl = lb + (1.0f - lb) * sigm(fz);
;         cp *= fl;
;         if (ckp && (s & 31) == 31 && s < 127) ckp[(s >> 5) * 128 + lane] = cp;
;         L[lane] = fl; L[64 + lane] = ql * sigm(ql);
;         f32x4 F[2][4], Q[2][4];
; #pragma unroll
;         for (int i = 0; i < 4; ++i) { F[0][i] = pf[i]; Q[0][i] = pf[16 + i]; }
;         const f2 v2 = {v, v}; f2 o2 = {0.f, 0.f}, o3 = {0.f, 0.f};
; #pragma unroll
;         for (int g = 0; g < 4; ++g) {
;             if (g < 3) {
; #pragma unroll
;                 for (int i = 0; i < 4; ++i) { F[(g + 1) & 1][i] = pf[(g + 1) * 4 + i]; Q[(g + 1) & 1][i] = pf[16 + (g + 1) * 4 + i]; } }
;             __builtin_amdgcn_sched_barrier(0);
; #pragma unroll
;             for (int i = 0; i < 4; ++i) {
;                 const f32x4 f4 = F[g & 1][i], q4 = Q[g & 1][i]; const int idx = (g * 4 + i) * 2;
;                 const f2 f01 = {f4[0], f4[1]}, f23 = {f4[2], f4[3]}, q01 = {q4[0], q4[1]}, q23 = {q4[2], q4[3]};
;                 S[idx] = pfma(f01, S[idx] - v2, v2); o2 = pfma(S[idx], q01, o2);
;                 S[idx + 1] = pfma(f23, S[idx + 1] - v2, v2); o3 = pfma(S[idx + 1], q23, o3);
;             }
;         }
;         OHp[(size_t)(t0 + s) * 512 + h * 128 + half * 64 + lane] = f2bf((o2[0] + o2[1]) + (o3[0] + o3[1]));
	v_pk_fma_f32 v[62:63], v[206:207], v[62:63], v[250:251] op_sel_hi:[1,1,0]
	v_pk_fma_f32 v[240:241], v[56:57], v[216:217], v[240:241]
	v_pk_fma_f32 v[244:245], v[58:59], v[218:219], v[244:245]
	v_pk_fma_f32 v[240:241], v[60:61], v[220:221], v[240:241]
	v_pk_fma_f32 v[244:245], v[62:63], v[222:223], v[244:245]
	v_pk_add_f32 v[112:113], v[112:113], v[250:251] op_sel:[0,1] op_sel_hi:[1,1] neg_lo:[0,1] neg_hi:[0,1]
	v_pk_add_f32 v[114:115], v[114:115], v[250:251] op_sel:[0,1] op_sel_hi:[1,1] neg_lo:[0,1] neg_hi:[0,1]
	v_pk_add_f32 v[116:117], v[116:117], v[250:251] op_sel:[0,1] op_sel_hi:[1,1] neg_lo:[0,1] neg_hi:[0,1]
	v_pk_add_f32 v[118:119], v[118:119], v[250:251] op_sel:[0,1] op_sel_hi:[1,1] neg_lo:[0,1] neg_hi:[0,1]
	v_pk_fma_f32 v[112:113], v[192:193], v[112:113], v[250:251] op_sel:[0,0,1] op_sel_hi:[1,1,1]
	v_pk_fma_f32 v[114:115], v[194:195], v[114:115], v[250:251] op_sel:[0,0,1] op_sel_hi:[1,1,1]
	v_pk_fma_f32 v[116:117], v[196:197], v[116:117], v[250:251] op_sel:[0,0,1] op_sel_hi:[1,1,1]
	v_pk_fma_f32 v[118:119], v[198:199], v[118:119], v[250:251] op_sel:[0,0,1] op_sel_hi:[1,1,1]
	v_pk_fma_f32 v[246:247], v[112:113], v[208:209], v[246:247]
	v_pk_fma_f32 v[248:249], v[114:115], v[210:211], v[248:249]
	v_pk_fma_f32 v[246:247], v[116:117], v[212:213], v[246:247]
	v_pk_fma_f32 v[248:249], v[118:119], v[214:215], v[248:249]
	v_pk_add_f32 v[120:121], v[120:121], v[250:251] op_sel:[0,1] op_sel_hi:[1,1] neg_lo:[0,1] neg_hi:[0,1]
	v_pk_add_f32 v[122:123], v[122:123], v[250:251] op_sel:[0,1] op_sel_hi:[1,1] neg_lo:[0,1] neg_hi:[0,1]
	v_pk_add_f32 v[124:125], v[124:125], v[250:251] op_sel:[0,1] op_sel_hi:[1,1] neg_lo:[0,1] neg_hi:[0,1]
	v_pk_add_f32 v[126:127], v[126:127], v[250:251] op_sel:[0,1] op_sel_hi:[1,1] neg_lo:[0,1] neg_hi:[0,1]
	v_pk_fma_f32 v[120:121], v[200:201], v[120:121], v[250:251] op_sel:[0,0,1] op_sel_hi:[1,1,1]
	v_pk_fma_f32 v[122:123], v[202:203], v[122:123], v[250:251] op_sel:[0,0,1] op_sel_hi:[1,1,1]
	v_pk_fma_f32 v[124:125], v[204:205], v[124:125], v[250:251] op_sel:[0,0,1] op_sel_hi:[1,1,1]
	v_pk_fma_f32 v[126:127], v[206:207], v[126:127], v[250:251] op_sel:[0,0,1] op_sel_hi:[1,1,1]
	v_pk_fma_f32 v[246:247], v[120:121], v[216:217], v[246:247]
	v_pk_fma_f32 v[248:249], v[122:123], v[218:219], v[248:249]
	v_pk_fma_f32 v[246:247], v[124:125], v[220:221], v[246:247]
	v_pk_fma_f32 v[248:249], v[126:127], v[222:223], v[248:249]
	v_add_f32_e32 v240, v240, v241
	v_add_f32_e32 v244, v244, v245
	v_add_f32_e32 v240, v240, v244
	v_bfe_u32 v244, v240, 16, 1
	v_add3_u32 v240, v240, v244, s69
	global_store_short_d16_hi v138, v240, s[26:27]
	v_add_f32_e32 v246, v246, v247
	v_add_f32_e32 v248, v248, v249
	v_add_f32_e32 v246, v246, v248
	v_bfe_u32 v248, v246, 16, 1
	v_add3_u32 v246, v246, v248, s69
	global_store_short_d16_hi v138, v246, s[26:27] offset:128
	v_mov_b32_e32 v250, v252
	v_mov_b32_e32 v251, v253
	v_add_u32_e32 v138, 0x400, v138
	global_load_ushort v236, v136, s[24:25]
	global_load_ushort v237, v136, s[24:25] offset:1024
	global_load_ushort v238, v137, s[24:25]
	global_load_ushort v239, v137, s[24:25] offset:128
	v_add_u32_e32 v136, 0x1000, v136
	v_add_u32_e32 v137, 0x1000, v137
	v_mov_b32_e32 v133, v132
	s_cmp_lg_u32 s36, 32
	s_cbranch_scc1 .Lhs_m_nock
	s_and_b32 s0, s37, 7
	s_cmp_lg_u32 s0, 7
	s_cbranch_scc1 .Lhs_m_nock
	s_cmp_eq_u32 s37, 31
	s_cbranch_scc1 .Lhs_m_nock
	s_lshr_b32 s0, s37, 3
	s_lshl_b32 s0, s0, 9
	s_add_u32 s0, s42, s0
	s_addc_u32 s1, s43, 0
	global_store_dword v147, v133, s[0:1]
.Lhs_m_nock:
	ds_read_b128 v[192:195], v135 offset:576
	ds_read_b128 v[196:199], v135 offset:592
	ds_read_b128 v[200:203], v135 offset:608
	ds_read_b128 v[204:207], v135 offset:624
	ds_read_b128 v[208:211], v135 offset:832
	ds_read_b128 v[212:215], v135 offset:848
	ds_read_b128 v[216:219], v135 offset:864
	ds_read_b128 v[220:223], v135 offset:880
	s_waitcnt lgkmcnt(8)
	v_pk_add_f32 v[0:1], v[0:1], v[250:251] op_sel_hi:[1,0] neg_lo:[0,1] neg_hi:[0,1]
	v_pk_add_f32 v[2:3], v[2:3], v[250:251] op_sel_hi:[1,0] neg_lo:[0,1] neg_hi:[0,1]
	v_pk_add_f32 v[4:5], v[4:5], v[250:251] op_sel_hi:[1,0] neg_lo:[0,1] neg_hi:[0,1]
	v_pk_add_f32 v[6:7], v[6:7], v[250:251] op_sel_hi:[1,0] neg_lo:[0,1] neg_hi:[0,1]
	v_pk_fma_f32 v[0:1], v[148:149], v[0:1], v[250:251] op_sel_hi:[1,1,0]
	v_pk_fma_f32 v[2:3], v[150:151], v[2:3], v[250:251] op_sel_hi:[1,1,0]
	v_pk_fma_f32 v[4:5], v[152:153], v[4:5], v[250:251] op_sel_hi:[1,1,0]
	v_pk_fma_f32 v[6:7], v[154:155], v[6:7], v[250:251] op_sel_hi:[1,1,0]
	v_pk_fma_f32 v[240:241], v[0:1], v[164:165], 0 op_sel_hi:[1,1,0]
	v_pk_fma_f32 v[244:245], v[2:3], v[166:167], 0 op_sel_hi:[1,1,0]
	v_pk_fma_f32 v[240:241], v[4:5], v[168:169], v[240:241]
	v_pk_fma_f32 v[244:245], v[6:7], v[170:171], v[244:245]
	v_pk_add_f32 v[8:9], v[8:9], v[250:251] op_sel_hi:[1,0] neg_lo:[0,1] neg_hi:[0,1]
	v_pk_add_f32 v[10:11], v[10:11], v[250:251] op_sel_hi:[1,0] neg_lo:[0,1] neg_hi:[0,1]
	v_pk_add_f32 v[12:13], v[12:13], v[250:251] op_sel_hi:[1,0] neg_lo:[0,1] neg_hi:[0,1]
	v_pk_add_f32 v[14:15], v[14:15], v[250:251] op_sel_hi:[1,0] neg_lo:[0,1] neg_hi:[0,1]
	v_pk_fma_f32 v[8:9], v[156:157], v[8:9], v[250:251] op_sel_hi:[1,1,0]
	v_pk_fma_f32 v[10:11], v[158:159], v[10:11], v[250:251] op_sel_hi:[1,1,0]
	v_pk_fma_f32 v[12:13], v[160:161], v[12:13], v[250:251] op_sel_hi:[1,1,0]
	v_pk_fma_f32 v[14:15], v[162:163], v[14:15], v[250:251] op_sel_hi:[1,1,0]
	v_pk_fma_f32 v[240:241], v[8:9], v[172:173], v[240:241]
	v_pk_fma_f32 v[244:245], v[10:11], v[174:175], v[244:245]
	v_pk_fma_f32 v[240:241], v[12:13], v[176:177], v[240:241]
	v_pk_fma_f32 v[244:245], v[14:15], v[178:179], v[244:245]
	v_pk_add_f32 v[64:65], v[64:65], v[250:251] op_sel:[0,1] op_sel_hi:[1,1] neg_lo:[0,1] neg_hi:[0,1]
; __device__ __forceinline__ float bf2f(unsigned short b) { return __uint_as_float((unsigned)b << 16); }
; __device__ __forceinline__ float sigm(float x) { return __builtin_amdgcn_rcpf(1.0f + __expf(-x)); }
; __device__ __forceinline__ f2 pfma(f2 a, f2 b, f2 c) { return __builtin_elementwise_fma(a, b, c); }
; __device__ __forceinline__ void hgrn_scan(const bf16_t* __restrict__ PH, int t0, int nsteps, int h, int half, int kh, int lane, float lb, f2 (&S)[32], float& cp, bf16_t* __restrict__ OHp, float* __restrict__ ckp, LAS float* L) {
;     ...
;     for (int s = 0; s < nsteps; ++s) {
;         const float ql = bf2f(q1[0]), fz = bf2f(q1[1]), v = bf2f(q1[2]);
; #pragma unroll
;         for (int j = 0; j < 3; ++j) { q1[j] = q2[j]; q2[j] = q3[j]; }
;         { const bf16_t* r = row + (size_t)(s + 3 < nsteps ? s + 3 : nsteps - 1) * 2048; q3[0] = r[0]; q3[1] = r[512]; q3[2] = r[voff]; }
;         const float fl = lb + (1.0f - lb) * sigm(fz);
;         cp *= fl;
;         if (ckp && (s & 31) == 31 && s < 127) ckp[(s >> 5) * 128 + lane] = cp;
;         L[lane] = fl; L[64 + lane] = ql * sigm(ql);
;         f32x4 F[2][4], Q[2][4];
; #pragma unroll
;         for (int i = 0; i < 4; ++i) { F[0][i] = pf[i]; Q[0][i] = pf[16 + i]; }
;         const f2 v2 = {v, v}; f2 o2 = {0.f, 0.f}, o3 = {0.f, 0.f};
; #pragma unroll
;         for (int g = 0; g < 4; ++g) {
;             if (g < 3) {
; #pragma unroll
;                 for (int i = 0; i < 4; ++i) { F[(g + 1) & 1][i] = pf[(g + 1) * 4 + i]; Q[(g + 1) & 1][i] = pf[16 + (g + 1) * 4 + i]; } }
;             __builtin_amdgcn_sched_barrier(0);
; #pragma unroll
;             for (int i = 0; i < 4; ++i) {
;                 const f32x4 f4 = F[g & 1][i], q4 = Q[g & 1][i]; const int idx = (g * 4 + i) * 2;
;                 const f2 f01 = {f4[0], f4[1]}, f23 = {f4[2], f4[3]}, q01 = {q4[0], q4[1]}, q23 = {q4[2], q4[3]};
;                 S[idx] = pfma(f01, S[idx] - v2, v2); o2 = pfma(S[idx], q01, o2);
;                 S[idx + 1] = pfma(f23, S[idx + 1] - v2, v2); o3 = pfma(S[idx + 1], q23, o3);
;             }
	v_pk_add_f32 v[66:67], v[66:67], v[250:251] op_sel:[0,1] op_sel_hi:[1,1] neg_lo:[0,1] neg_hi:[0,1]
	v_pk_add_f32 v[68:69], v[68:69], v[250:251] op_sel:[0,1] op_sel_hi:[1,1] neg_lo:[0,1] neg_hi:[0,1]
	v_pk_add_f32 v[70:71], v[70:71], v[250:251] op_sel:[0,1] op_sel_hi:[1,1] neg_lo:[0,1] neg_hi:[0,1]
	v_pk_fma_f32 v[64:65], v[148:149], v[64:65], v[250:251] op_sel:[0,0,1] op_sel_hi:[1,1,1]
	v_pk_fma_f32 v[66:67], v[150:151], v[66:67], v[250:251] op_sel:[0,0,1] op_sel_hi:[1,1,1]
	v_pk_fma_f32 v[68:69], v[152:153], v[68:69], v[250:251] op_sel:[0,0,1] op_sel_hi:[1,1,1]
	v_pk_fma_f32 v[70:71], v[154:155], v[70:71], v[250:251] op_sel:[0,0,1] op_sel_hi:[1,1,1]
	v_pk_fma_f32 v[246:247], v[64:65], v[164:165], 0 op_sel_hi:[1,1,0]
	v_pk_fma_f32 v[248:249], v[66:67], v[166:167], 0 op_sel_hi:[1,1,0]
	v_pk_fma_f32 v[246:247], v[68:69], v[168:169], v[246:247]
	v_pk_fma_f32 v[248:249], v[70:71], v[170:171], v[248:249]
	v_pk_add_f32 v[72:73], v[72:73], v[250:251] op_sel:[0,1] op_sel_hi:[1,1] neg_lo:[0,1] neg_hi:[0,1]
	v_pk_add_f32 v[74:75], v[74:75], v[250:251] op_sel:[0,1] op_sel_hi:[1,1] neg_lo:[0,1] neg_hi:[0,1]
	v_pk_add_f32 v[76:77], v[76:77], v[250:251] op_sel:[0,1] op_sel_hi:[1,1] neg_lo:[0,1] neg_hi:[0,1]
	v_pk_add_f32 v[78:79], v[78:79], v[250:251] op_sel:[0,1] op_sel_hi:[1,1] neg_lo:[0,1] neg_hi:[0,1]
	v_pk_fma_f32 v[72:73], v[156:157], v[72:73], v[250:251] op_sel:[0,0,1] op_sel_hi:[1,1,1]
	v_pk_fma_f32 v[74:75], v[158:159], v[74:75], v[250:251] op_sel:[0,0,1] op_sel_hi:[1,1,1]
	v_pk_fma_f32 v[76:77], v[160:161], v[76:77], v[250:251] op_sel:[0,0,1] op_sel_hi:[1,1,1]
	v_pk_fma_f32 v[78:79], v[162:163], v[78:79], v[250:251] op_sel:[0,0,1] op_sel_hi:[1,1,1]
	v_pk_fma_f32 v[246:247], v[72:73], v[172:173], v[246:247]
	v_pk_fma_f32 v[248:249], v[74:75], v[174:175], v[248:249]
	v_pk_fma_f32 v[246:247], v[76:77], v[176:177], v[246:247]
	v_pk_fma_f32 v[248:249], v[78:79], v[178:179], v[248:249]
	s_waitcnt vmcnt(18)
	v_lshlrev_b32_e32 v140, 16, v225
	v_lshlrev_b32_e32 v141, 16, v224
	v_mul_f32_e32 v142, 0xbfb8aa3b, v140
	v_mul_f32_e32 v143, 0xbfb8aa3b, v141
	v_exp_f32_e32 v142, v142
	v_exp_f32_e32 v143, v143
	v_lshlrev_b32_e32 v252, 16, v226
	v_lshlrev_b32_e32 v253, 16, v227
	v_add_f32_e32 v142, 1.0, v142
	v_add_f32_e32 v143, 1.0, v143
	v_rcp_f32_e32 v142, v142
	v_rcp_f32_e32 v143, v143
	v_fma_f32 v142, v131, v142, v130
	v_mul_f32_e32 v143, v143, v141
	v_mul_f32_e32 v132, v132, v142
	ds_write2st64_b32 v134, v142, v143 offset0:0 offset1:1
	ds_read_b128 v[148:151], v135 offset:640
	ds_read_b128 v[152:155], v135 offset:656
	ds_read_b128 v[156:159], v135 offset:672
	ds_read_b128 v[160:163], v135 offset:688
	ds_read_b128 v[164:167], v135 offset:896
	ds_read_b128 v[168:171], v135 offset:912
	ds_read_b128 v[172:175], v135 offset:928
	ds_read_b128 v[176:179], v135 offset:944
	s_waitcnt lgkmcnt(9)
	v_pk_add_f32 v[16:17], v[16:17], v[250:251] op_sel_hi:[1,0] neg_lo:[0,1] neg_hi:[0,1]
	v_pk_add_f32 v[18:19], v[18:19], v[250:251] op_sel_hi:[1,0] neg_lo:[0,1] neg_hi:[0,1]
	v_pk_add_f32 v[20:21], v[20:21], v[250:251] op_sel_hi:[1,0] neg_lo:[0,1] neg_hi:[0,1]
	v_pk_add_f32 v[22:23], v[22:23], v[250:251] op_sel_hi:[1,0] neg_lo:[0,1] neg_hi:[0,1]
	v_pk_fma_f32 v[16:17], v[192:193], v[16:17], v[250:251] op_sel_hi:[1,1,0]
	v_pk_fma_f32 v[18:19], v[194:195], v[18:19], v[250:251] op_sel_hi:[1,1,0]
	v_pk_fma_f32 v[20:21], v[196:197], v[20:21], v[250:251] op_sel_hi:[1,1,0]
	v_pk_fma_f32 v[22:23], v[198:199], v[22:23], v[250:251] op_sel_hi:[1,1,0]
	v_pk_fma_f32 v[240:241], v[16:17], v[208:209], v[240:241]
	v_pk_fma_f32 v[244:245], v[18:19], v[210:211], v[244:245]
	v_pk_fma_f32 v[240:241], v[20:21], v[212:213], v[240:241]
	v_pk_fma_f32 v[244:245], v[22:23], v[214:215], v[244:245]
	v_pk_add_f32 v[24:25], v[24:25], v[250:251] op_sel_hi:[1,0] neg_lo:[0,1] neg_hi:[0,1]
	v_pk_add_f32 v[26:27], v[26:27], v[250:251] op_sel_hi:[1,0] neg_lo:[0,1] neg_hi:[0,1]
	v_pk_add_f32 v[28:29], v[28:29], v[250:251] op_sel_hi:[1,0] neg_lo:[0,1] neg_hi:[0,1]
	v_pk_add_f32 v[30:31], v[30:31], v[250:251] op_sel_hi:[1,0] neg_lo:[0,1] neg_hi:[0,1]
	v_pk_fma_f32 v[24:25], v[200:201], v[24:25], v[250:251] op_sel_hi:[1,1,0]
	v_pk_fma_f32 v[26:27], v[202:203], v[26:27], v[250:251] op_sel_hi:[1,1,0]
	v_pk_fma_f32 v[28:29], v[204:205], v[28:29], v[250:251] op_sel_hi:[1,1,0]
	v_pk_fma_f32 v[30:31], v[206:207], v[30:31], v[250:251] op_sel_hi:[1,1,0]
	v_pk_fma_f32 v[240:241], v[24:25], v[216:217], v[240:241]
	v_pk_fma_f32 v[244:245], v[26:27], v[218:219], v[244:245]
	v_pk_fma_f32 v[240:241], v[28:29], v[220:221], v[240:241]
	v_pk_fma_f32 v[244:245], v[30:31], v[222:223], v[244:245]
	v_pk_add_f32 v[80:81], v[80:81], v[250:251] op_sel:[0,1] op_sel_hi:[1,1] neg_lo:[0,1] neg_hi:[0,1]
	v_pk_add_f32 v[82:83], v[82:83], v[250:251] op_sel:[0,1] op_sel_hi:[1,1] neg_lo:[0,1] neg_hi:[0,1]
	v_pk_add_f32 v[84:85], v[84:85], v[250:251] op_sel:[0,1] op_sel_hi:[1,1] neg_lo:[0,1] neg_hi:[0,1]
	v_pk_add_f32 v[86:87], v[86:87], v[250:251] op_sel:[0,1] op_sel_hi:[1,1] neg_lo:[0,1] neg_hi:[0,1]
	v_pk_fma_f32 v[80:81], v[192:193], v[80:81], v[250:251] op_sel:[0,0,1] op_sel_hi:[1,1,1]
	v_pk_fma_f32 v[82:83], v[194:195], v[82:83], v[250:251] op_sel:[0,0,1] op_sel_hi:[1,1,1]
	v_pk_fma_f32 v[84:85], v[196:197], v[84:85], v[250:251] op_sel:[0,0,1] op_sel_hi:[1,1,1]
	v_pk_fma_f32 v[86:87], v[198:199], v[86:87], v[250:251] op_sel:[0,0,1] op_sel_hi:[1,1,1]
	v_pk_fma_f32 v[246:247], v[80:81], v[208:209], v[246:247]
	v_pk_fma_f32 v[248:249], v[82:83], v[210:211], v[248:249]
	v_pk_fma_f32 v[246:247], v[84:85], v[212:213], v[246:247]
	v_pk_fma_f32 v[248:249], v[86:87], v[214:215], v[248:249]
	v_pk_add_f32 v[88:89], v[88:89], v[250:251] op_sel:[0,1] op_sel_hi:[1,1] neg_lo:[0,1] neg_hi:[0,1]
	v_pk_add_f32 v[90:91], v[90:91], v[250:251] op_sel:[0,1] op_sel_hi:[1,1] neg_lo:[0,1] neg_hi:[0,1]
	v_pk_add_f32 v[92:93], v[92:93], v[250:251] op_sel:[0,1] op_sel_hi:[1,1] neg_lo:[0,1] neg_hi:[0,1]
	v_pk_add_f32 v[94:95], v[94:95], v[250:251] op_sel:[0,1] op_sel_hi:[1,1] neg_lo:[0,1] neg_hi:[0,1]
	v_pk_fma_f32 v[88:89], v[200:201], v[88:89], v[250:251] op_sel:[0,0,1] op_sel_hi:[1,1,1]
	v_pk_fma_f32 v[90:91], v[202:203], v[90:91], v[250:251] op_sel:[0,0,1] op_sel_hi:[1,1,1]
	v_pk_fma_f32 v[92:93], v[204:205], v[92:93], v[250:251] op_sel:[0,0,1] op_sel_hi:[1,1,1]
	v_pk_fma_f32 v[94:95], v[206:207], v[94:95], v[250:251] op_sel:[0,0,1] op_sel_hi:[1,1,1]
	v_pk_fma_f32 v[246:247], v[88:89], v[216:217], v[246:247]
	v_pk_fma_f32 v[248:249], v[90:91], v[218:219], v[248:249]
	v_pk_fma_f32 v[246:247], v[92:93], v[220:221], v[246:247]
	v_pk_fma_f32 v[248:249], v[94:95], v[222:223], v[248:249]
	ds_read_b128 v[192:195], v135 offset:704
	ds_read_b128 v[196:199], v135 offset:720
	ds_read_b128 v[200:203], v135 offset:736
	ds_read_b128 v[204:207], v135 offset:752
	ds_read_b128 v[208:211], v135 offset:960
	ds_read_b128 v[212:215], v135 offset:976
	ds_read_b128 v[216:219], v135 offset:992
	ds_read_b128 v[220:223], v135 offset:1008
	s_waitcnt lgkmcnt(8)
; __device__ __forceinline__ f2 pfma(f2 a, f2 b, f2 c) { return __builtin_elementwise_fma(a, b, c); }
; __device__ __forceinline__ void hgrn_scan(const bf16_t* __restrict__ PH, int t0, int nsteps, int h, int half, int kh, int lane, float lb, f2 (&S)[32], float& cp, bf16_t* __restrict__ OHp, float* __restrict__ ckp, LAS float* L) {
;     ...
;         for (int g = 0; g < 4; ++g) {
;             if (g < 3) {
; #pragma unroll
;                 for (int i = 0; i < 4; ++i) { F[(g + 1) & 1][i] = pf[(g + 1) * 4 + i]; Q[(g + 1) & 1][i] = pf[16 + (g + 1) * 4 + i]; } }
;             __builtin_amdgcn_sched_barrier(0);
; #pragma unroll
;             for (int i = 0; i < 4; ++i) {
;                 const f32x4 f4 = F[g & 1][i], q4 = Q[g & 1][i]; const int idx = (g * 4 + i) * 2;
;                 const f2 f01 = {f4[0], f4[1]}, f23 = {f4[2], f4[3]}, q01 = {q4[0], q4[1]}, q23 = {q4[2], q4[3]};
;                 S[idx] = pfma(f01, S[idx] - v2, v2); o2 = pfma(S[idx], q01, o2);
;                 S[idx + 1] = pfma(f23, S[idx + 1] - v2, v2); o3 = pfma(S[idx + 1], q23, o3);
;             }
	v_pk_add_f32 v[32:33], v[32:33], v[250:251] op_sel_hi:[1,0] neg_lo:[0,1] neg_hi:[0,1]
	v_pk_add_f32 v[34:35], v[34:35], v[250:251] op_sel_hi:[1,0] neg_lo:[0,1] neg_hi:[0,1]
	v_pk_add_f32 v[36:37], v[36:37], v[250:251] op_sel_hi:[1,0] neg_lo:[0,1] neg_hi:[0,1]
	v_pk_add_f32 v[38:39], v[38:39], v[250:251] op_sel_hi:[1,0] neg_lo:[0,1] neg_hi:[0,1]
	v_pk_fma_f32 v[32:33], v[148:149], v[32:33], v[250:251] op_sel_hi:[1,1,0]
	v_pk_fma_f32 v[34:35], v[150:151], v[34:35], v[250:251] op_sel_hi:[1,1,0]
	v_pk_fma_f32 v[36:37], v[152:153], v[36:37], v[250:251] op_sel_hi:[1,1,0]
	v_pk_fma_f32 v[38:39], v[154:155], v[38:39], v[250:251] op_sel_hi:[1,1,0]
	v_pk_fma_f32 v[240:241], v[32:33], v[164:165], v[240:241]
	v_pk_fma_f32 v[244:245], v[34:35], v[166:167], v[244:245]
	v_pk_fma_f32 v[240:241], v[36:37], v[168:169], v[240:241]
	v_pk_fma_f32 v[244:245], v[38:39], v[170:171], v[244:245]
	v_pk_add_f32 v[40:41], v[40:41], v[250:251] op_sel_hi:[1,0] neg_lo:[0,1] neg_hi:[0,1]
	v_pk_add_f32 v[42:43], v[42:43], v[250:251] op_sel_hi:[1,0] neg_lo:[0,1] neg_hi:[0,1]
	v_pk_add_f32 v[44:45], v[44:45], v[250:251] op_sel_hi:[1,0] neg_lo:[0,1] neg_hi:[0,1]
	v_pk_add_f32 v[46:47], v[46:47], v[250:251] op_sel_hi:[1,0] neg_lo:[0,1] neg_hi:[0,1]
	v_pk_fma_f32 v[40:41], v[156:157], v[40:41], v[250:251] op_sel_hi:[1,1,0]
	v_pk_fma_f32 v[42:43], v[158:159], v[42:43], v[250:251] op_sel_hi:[1,1,0]
	v_pk_fma_f32 v[44:45], v[160:161], v[44:45], v[250:251] op_sel_hi:[1,1,0]
	v_pk_fma_f32 v[46:47], v[162:163], v[46:47], v[250:251] op_sel_hi:[1,1,0]
	v_pk_fma_f32 v[240:241], v[40:41], v[172:173], v[240:241]
	v_pk_fma_f32 v[244:245], v[42:43], v[174:175], v[244:245]
	v_pk_fma_f32 v[240:241], v[44:45], v[176:177], v[240:241]
	v_pk_fma_f32 v[244:245], v[46:47], v[178:179], v[244:245]
	v_pk_add_f32 v[96:97], v[96:97], v[250:251] op_sel:[0,1] op_sel_hi:[1,1] neg_lo:[0,1] neg_hi:[0,1]
	v_pk_add_f32 v[98:99], v[98:99], v[250:251] op_sel:[0,1] op_sel_hi:[1,1] neg_lo:[0,1] neg_hi:[0,1]
	v_pk_add_f32 v[100:101], v[100:101], v[250:251] op_sel:[0,1] op_sel_hi:[1,1] neg_lo:[0,1] neg_hi:[0,1]
	v_pk_add_f32 v[102:103], v[102:103], v[250:251] op_sel:[0,1] op_sel_hi:[1,1] neg_lo:[0,1] neg_hi:[0,1]
	v_pk_fma_f32 v[96:97], v[148:149], v[96:97], v[250:251] op_sel:[0,0,1] op_sel_hi:[1,1,1]
	v_pk_fma_f32 v[98:99], v[150:151], v[98:99], v[250:251] op_sel:[0,0,1] op_sel_hi:[1,1,1]
	v_pk_fma_f32 v[100:101], v[152:153], v[100:101], v[250:251] op_sel:[0,0,1] op_sel_hi:[1,1,1]
	v_pk_fma_f32 v[102:103], v[154:155], v[102:103], v[250:251] op_sel:[0,0,1] op_sel_hi:[1,1,1]
	v_pk_fma_f32 v[246:247], v[96:97], v[164:165], v[246:247]
	v_pk_fma_f32 v[248:249], v[98:99], v[166:167], v[248:249]
	v_pk_fma_f32 v[246:247], v[100:101], v[168:169], v[246:247]
	v_pk_fma_f32 v[248:249], v[102:103], v[170:171], v[248:249]
	v_pk_add_f32 v[104:105], v[104:105], v[250:251] op_sel:[0,1] op_sel_hi:[1,1] neg_lo:[0,1] neg_hi:[0,1]
	v_pk_add_f32 v[106:107], v[106:107], v[250:251] op_sel:[0,1] op_sel_hi:[1,1] neg_lo:[0,1] neg_hi:[0,1]
	v_pk_add_f32 v[108:109], v[108:109], v[250:251] op_sel:[0,1] op_sel_hi:[1,1] neg_lo:[0,1] neg_hi:[0,1]
	v_pk_add_f32 v[110:111], v[110:111], v[250:251] op_sel:[0,1] op_sel_hi:[1,1] neg_lo:[0,1] neg_hi:[0,1]
	v_pk_fma_f32 v[104:105], v[156:157], v[104:105], v[250:251] op_sel:[0,0,1] op_sel_hi:[1,1,1]
	v_pk_fma_f32 v[106:107], v[158:159], v[106:107], v[250:251] op_sel:[0,0,1] op_sel_hi:[1,1,1]
	v_pk_fma_f32 v[108:109], v[160:161], v[108:109], v[250:251] op_sel:[0,0,1] op_sel_hi:[1,1,1]
	v_pk_fma_f32 v[110:111], v[162:163], v[110:111], v[250:251] op_sel:[0,0,1] op_sel_hi:[1,1,1]
	v_pk_fma_f32 v[246:247], v[104:105], v[172:173], v[246:247]
	v_pk_fma_f32 v[248:249], v[106:107], v[174:175], v[248:249]
	v_pk_fma_f32 v[246:247], v[108:109], v[176:177], v[246:247]
	v_pk_fma_f32 v[248:249], v[110:111], v[178:179], v[248:249]
	ds_read_b128 v[148:151], v135 offset:0
	ds_read_b128 v[152:155], v135 offset:16
	ds_read_b128 v[156:159], v135 offset:32
	ds_read_b128 v[160:163], v135 offset:48
	ds_read_b128 v[164:167], v135 offset:256
	ds_read_b128 v[168:171], v135 offset:272
	ds_read_b128 v[172:175], v135 offset:288
	ds_read_b128 v[176:179], v135 offset:304
	s_waitcnt lgkmcnt(8)
	v_pk_add_f32 v[48:49], v[48:49], v[250:251] op_sel_hi:[1,0] neg_lo:[0,1] neg_hi:[0,1]
	v_pk_add_f32 v[50:51], v[50:51], v[250:251] op_sel_hi:[1,0] neg_lo:[0,1] neg_hi:[0,1]
	v_pk_add_f32 v[52:53], v[52:53], v[250:251] op_sel_hi:[1,0] neg_lo:[0,1] neg_hi:[0,1]
	v_pk_add_f32 v[54:55], v[54:55], v[250:251] op_sel_hi:[1,0] neg_lo:[0,1] neg_hi:[0,1]
	v_pk_fma_f32 v[48:49], v[192:193], v[48:49], v[250:251] op_sel_hi:[1,1,0]
	v_pk_fma_f32 v[50:51], v[194:195], v[50:51], v[250:251] op_sel_hi:[1,1,0]
	v_pk_fma_f32 v[52:53], v[196:197], v[52:53], v[250:251] op_sel_hi:[1,1,0]
	v_pk_fma_f32 v[54:55], v[198:199], v[54:55], v[250:251] op_sel_hi:[1,1,0]
	v_pk_fma_f32 v[240:241], v[48:49], v[208:209], v[240:241]
	v_pk_fma_f32 v[244:245], v[50:51], v[210:211], v[244:245]
	v_pk_fma_f32 v[240:241], v[52:53], v[212:213], v[240:241]
	v_pk_fma_f32 v[244:245], v[54:55], v[214:215], v[244:245]
	v_pk_add_f32 v[56:57], v[56:57], v[250:251] op_sel_hi:[1,0] neg_lo:[0,1] neg_hi:[0,1]
	v_pk_add_f32 v[58:59], v[58:59], v[250:251] op_sel_hi:[1,0] neg_lo:[0,1] neg_hi:[0,1]
	v_pk_add_f32 v[60:61], v[60:61], v[250:251] op_sel_hi:[1,0] neg_lo:[0,1] neg_hi:[0,1]
	v_pk_add_f32 v[62:63], v[62:63], v[250:251] op_sel_hi:[1,0] neg_lo:[0,1] neg_hi:[0,1]
	v_pk_fma_f32 v[56:57], v[200:201], v[56:57], v[250:251] op_sel_hi:[1,1,0]
	v_pk_fma_f32 v[58:59], v[202:203], v[58:59], v[250:251] op_sel_hi:[1,1,0]
	v_pk_fma_f32 v[60:61], v[204:205], v[60:61], v[250:251] op_sel_hi:[1,1,0]
; __device__ __forceinline__ unsigned short f2bf(float f) { unsigned u = __float_as_uint(f); u += 0x7FFFu + ((u >> 16) & 1u); return (unsigned short)(u >> 16); }
; __device__ __forceinline__ f2 pfma(f2 a, f2 b, f2 c) { return __builtin_elementwise_fma(a, b, c); }
; __device__ __forceinline__ void hgrn_scan(const bf16_t* __restrict__ PH, int t0, int nsteps, int h, int half, int kh, int lane, float lb, f2 (&S)[32], float& cp, bf16_t* __restrict__ OHp, float* __restrict__ ckp, LAS float* L) {
;     ...
;             for (int i = 0; i < 4; ++i) {
;                 const f32x4 f4 = F[g & 1][i], q4 = Q[g & 1][i]; const int idx = (g * 4 + i) * 2;
;                 const f2 f01 = {f4[0], f4[1]}, f23 = {f4[2], f4[3]}, q01 = {q4[0], q4[1]}, q23 = {q4[2], q4[3]};
;                 S[idx] = pfma(f01, S[idx] - v2, v2); o2 = pfma(S[idx], q01, o2);
;                 S[idx + 1] = pfma(f23, S[idx + 1] - v2, v2); o3 = pfma(S[idx + 1], q23, o3);
;             }
;         }
;         OHp[(size_t)(t0 + s) * 512 + h * 128 + half * 64 + lane] = f2bf((o2[0] + o2[1]) + (o3[0] + o3[1]));
;     }
; __device__ void phase_hgrn_scan(const Ctx& p, int l, LAS unsigned char* lds) {
;     ...
;         float* up = UCH + (size_t)idx * 16384 + (size_t)(kh * 64) * 128 + half * 64 + lane;
; #pragma unroll
;         for (int k = 0; k < 32; ++k) { up[(2 * k) * 128] = S[k][0]; up[(2 * k + 1) * 128] = S[k][1]; }
;         if (half == 0) PGH[idx * 128 + kh * 64 + lane] = cp;
	v_pk_fma_f32 v[62:63], v[206:207], v[62:63], v[250:251] op_sel_hi:[1,1,0]
	v_pk_fma_f32 v[240:241], v[56:57], v[216:217], v[240:241]
	v_pk_fma_f32 v[244:245], v[58:59], v[218:219], v[244:245]
	v_pk_fma_f32 v[240:241], v[60:61], v[220:221], v[240:241]
	v_pk_fma_f32 v[244:245], v[62:63], v[222:223], v[244:245]
	v_pk_add_f32 v[112:113], v[112:113], v[250:251] op_sel:[0,1] op_sel_hi:[1,1] neg_lo:[0,1] neg_hi:[0,1]
	v_pk_add_f32 v[114:115], v[114:115], v[250:251] op_sel:[0,1] op_sel_hi:[1,1] neg_lo:[0,1] neg_hi:[0,1]
	v_pk_add_f32 v[116:117], v[116:117], v[250:251] op_sel:[0,1] op_sel_hi:[1,1] neg_lo:[0,1] neg_hi:[0,1]
	v_pk_add_f32 v[118:119], v[118:119], v[250:251] op_sel:[0,1] op_sel_hi:[1,1] neg_lo:[0,1] neg_hi:[0,1]
	v_pk_fma_f32 v[112:113], v[192:193], v[112:113], v[250:251] op_sel:[0,0,1] op_sel_hi:[1,1,1]
	v_pk_fma_f32 v[114:115], v[194:195], v[114:115], v[250:251] op_sel:[0,0,1] op_sel_hi:[1,1,1]
	v_pk_fma_f32 v[116:117], v[196:197], v[116:117], v[250:251] op_sel:[0,0,1] op_sel_hi:[1,1,1]
	v_pk_fma_f32 v[118:119], v[198:199], v[118:119], v[250:251] op_sel:[0,0,1] op_sel_hi:[1,1,1]
	v_pk_fma_f32 v[246:247], v[112:113], v[208:209], v[246:247]
	v_pk_fma_f32 v[248:249], v[114:115], v[210:211], v[248:249]
	v_pk_fma_f32 v[246:247], v[116:117], v[212:213], v[246:247]
	v_pk_fma_f32 v[248:249], v[118:119], v[214:215], v[248:249]
	v_pk_add_f32 v[120:121], v[120:121], v[250:251] op_sel:[0,1] op_sel_hi:[1,1] neg_lo:[0,1] neg_hi:[0,1]
	v_pk_add_f32 v[122:123], v[122:123], v[250:251] op_sel:[0,1] op_sel_hi:[1,1] neg_lo:[0,1] neg_hi:[0,1]
	v_pk_add_f32 v[124:125], v[124:125], v[250:251] op_sel:[0,1] op_sel_hi:[1,1] neg_lo:[0,1] neg_hi:[0,1]
	v_pk_add_f32 v[126:127], v[126:127], v[250:251] op_sel:[0,1] op_sel_hi:[1,1] neg_lo:[0,1] neg_hi:[0,1]
	v_pk_fma_f32 v[120:121], v[200:201], v[120:121], v[250:251] op_sel:[0,0,1] op_sel_hi:[1,1,1]
	v_pk_fma_f32 v[122:123], v[202:203], v[122:123], v[250:251] op_sel:[0,0,1] op_sel_hi:[1,1,1]
	v_pk_fma_f32 v[124:125], v[204:205], v[124:125], v[250:251] op_sel:[0,0,1] op_sel_hi:[1,1,1]
	v_pk_fma_f32 v[126:127], v[206:207], v[126:127], v[250:251] op_sel:[0,0,1] op_sel_hi:[1,1,1]
	v_pk_fma_f32 v[246:247], v[120:121], v[216:217], v[246:247]
	v_pk_fma_f32 v[248:249], v[122:123], v[218:219], v[248:249]
	v_pk_fma_f32 v[246:247], v[124:125], v[220:221], v[246:247]
	v_pk_fma_f32 v[248:249], v[126:127], v[222:223], v[248:249]
	v_add_f32_e32 v240, v240, v241
	v_add_f32_e32 v244, v244, v245
	v_add_f32_e32 v240, v240, v244
	v_bfe_u32 v244, v240, 16, 1
	v_add3_u32 v240, v240, v244, s69
	global_store_short_d16_hi v138, v240, s[26:27]
	v_add_f32_e32 v246, v246, v247
	v_add_f32_e32 v248, v248, v249
	v_add_f32_e32 v246, v246, v248
	v_bfe_u32 v248, v246, 16, 1
	v_add3_u32 v246, v246, v248, s69
	global_store_short_d16_hi v138, v246, s[26:27] offset:128
	v_mov_b32_e32 v250, v252
	v_mov_b32_e32 v251, v253
	v_add_u32_e32 v138, 0x400, v138
	s_add_i32 s37, s37, 1
	s_cmp_lg_u32 s37, s36
	s_cbranch_scc1 .Lhs_m_loop
	s_waitcnt vmcnt(0) lgkmcnt(0)
	s_cmp_eq_u32 s38, 4
	s_cbranch_scc1 .Lhs_store
	global_store_dword v147, v133, s[44:45]
.Lhs_store:
	global_store_dword v147, v0, s[40:41] offset:0
	global_store_dword v147, v64, s[40:41] offset:256
	global_store_dword v147, v1, s[40:41] offset:512
	global_store_dword v147, v65, s[40:41] offset:768
	global_store_dword v147, v2, s[40:41] offset:1024
	global_store_dword v147, v66, s[40:41] offset:1280
	global_store_dword v147, v3, s[40:41] offset:1536
	global_store_dword v147, v67, s[40:41] offset:1792
	global_store_dword v147, v4, s[40:41] offset:2048
	global_store_dword v147, v68, s[40:41] offset:2304
	global_store_dword v147, v5, s[40:41] offset:2560
	global_store_dword v147, v69, s[40:41] offset:2816
	global_store_dword v147, v6, s[40:41] offset:3072
	global_store_dword v147, v70, s[40:41] offset:3328
	global_store_dword v147, v7, s[40:41] offset:3584
	global_store_dword v147, v71, s[40:41] offset:3840
	v_add_u32_e32 v147, 0x1000, v147
	global_store_dword v147, v8, s[40:41] offset:0
	global_store_dword v147, v72, s[40:41] offset:256
	global_store_dword v147, v9, s[40:41] offset:512
	global_store_dword v147, v73, s[40:41] offset:768
	global_store_dword v147, v10, s[40:41] offset:1024
	global_store_dword v147, v74, s[40:41] offset:1280
	global_store_dword v147, v11, s[40:41] offset:1536
	global_store_dword v147, v75, s[40:41] offset:1792
	global_store_dword v147, v12, s[40:41] offset:2048
	global_store_dword v147, v76, s[40:41] offset:2304
	global_store_dword v147, v13, s[40:41] offset:2560
	global_store_dword v147, v77, s[40:41] offset:2816
	global_store_dword v147, v14, s[40:41] offset:3072
	global_store_dword v147, v78, s[40:41] offset:3328
	global_store_dword v147, v15, s[40:41] offset:3584
	global_store_dword v147, v79, s[40:41] offset:3840
	v_add_u32_e32 v147, 0x1000, v147
	global_store_dword v147, v16, s[40:41] offset:0
	global_store_dword v147, v80, s[40:41] offset:256
	global_store_dword v147, v17, s[40:41] offset:512
	global_store_dword v147, v81, s[40:41] offset:768
	global_store_dword v147, v18, s[40:41] offset:1024
	global_store_dword v147, v82, s[40:41] offset:1280
	global_store_dword v147, v19, s[40:41] offset:1536
; __device__ void phase_hgrn_scan(const Ctx& p, int l, LAS unsigned char* lds) {
;     ...
;         float* up = UCH + (size_t)idx * 16384 + (size_t)(kh * 64) * 128 + half * 64 + lane;
; #pragma unroll
;         for (int k = 0; k < 32; ++k) { up[(2 * k) * 128] = S[k][0]; up[(2 * k + 1) * 128] = S[k][1]; }
;         if (half == 0) PGH[idx * 128 + kh * 64 + lane] = cp;
	global_store_dword v147, v83, s[40:41] offset:1792
	global_store_dword v147, v20, s[40:41] offset:2048
	global_store_dword v147, v84, s[40:41] offset:2304
	global_store_dword v147, v21, s[40:41] offset:2560
	global_store_dword v147, v85, s[40:41] offset:2816
	global_store_dword v147, v22, s[40:41] offset:3072
	global_store_dword v147, v86, s[40:41] offset:3328
	global_store_dword v147, v23, s[40:41] offset:3584
	global_store_dword v147, v87, s[40:41] offset:3840
	v_add_u32_e32 v147, 0x1000, v147
	global_store_dword v147, v24, s[40:41] offset:0
	global_store_dword v147, v88, s[40:41] offset:256
	global_store_dword v147, v25, s[40:41] offset:512
	global_store_dword v147, v89, s[40:41] offset:768
	global_store_dword v147, v26, s[40:41] offset:1024
	global_store_dword v147, v90, s[40:41] offset:1280
	global_store_dword v147, v27, s[40:41] offset:1536
	global_store_dword v147, v91, s[40:41] offset:1792
	global_store_dword v147, v28, s[40:41] offset:2048
	global_store_dword v147, v92, s[40:41] offset:2304
	global_store_dword v147, v29, s[40:41] offset:2560
	global_store_dword v147, v93, s[40:41] offset:2816
	global_store_dword v147, v30, s[40:41] offset:3072
	global_store_dword v147, v94, s[40:41] offset:3328
	global_store_dword v147, v31, s[40:41] offset:3584
	global_store_dword v147, v95, s[40:41] offset:3840
	v_add_u32_e32 v147, 0x1000, v147
	global_store_dword v147, v32, s[40:41] offset:0
	global_store_dword v147, v96, s[40:41] offset:256
	global_store_dword v147, v33, s[40:41] offset:512
	global_store_dword v147, v97, s[40:41] offset:768
	global_store_dword v147, v34, s[40:41] offset:1024
	global_store_dword v147, v98, s[40:41] offset:1280
	global_store_dword v147, v35, s[40:41] offset:1536
	global_store_dword v147, v99, s[40:41] offset:1792
	global_store_dword v147, v36, s[40:41] offset:2048
	global_store_dword v147, v100, s[40:41] offset:2304
	global_store_dword v147, v37, s[40:41] offset:2560
	global_store_dword v147, v101, s[40:41] offset:2816
	global_store_dword v147, v38, s[40:41] offset:3072
	global_store_dword v147, v102, s[40:41] offset:3328
	global_store_dword v147, v39, s[40:41] offset:3584
	global_store_dword v147, v103, s[40:41] offset:3840
	v_add_u32_e32 v147, 0x1000, v147
	global_store_dword v147, v40, s[40:41] offset:0
	global_store_dword v147, v104, s[40:41] offset:256
	global_store_dword v147, v41, s[40:41] offset:512
	global_store_dword v147, v105, s[40:41] offset:768
	global_store_dword v147, v42, s[40:41] offset:1024
	global_store_dword v147, v106, s[40:41] offset:1280
	global_store_dword v147, v43, s[40:41] offset:1536
	global_store_dword v147, v107, s[40:41] offset:1792
	global_store_dword v147, v44, s[40:41] offset:2048
	global_store_dword v147, v108, s[40:41] offset:2304
	global_store_dword v147, v45, s[40:41] offset:2560
	global_store_dword v147, v109, s[40:41] offset:2816
	global_store_dword v147, v46, s[40:41] offset:3072
	global_store_dword v147, v110, s[40:41] offset:3328
	global_store_dword v147, v47, s[40:41] offset:3584
	global_store_dword v147, v111, s[40:41] offset:3840
	v_add_u32_e32 v147, 0x1000, v147
	global_store_dword v147, v48, s[40:41] offset:0
	global_store_dword v147, v112, s[40:41] offset:256
	global_store_dword v147, v49, s[40:41] offset:512
	global_store_dword v147, v113, s[40:41] offset:768
	global_store_dword v147, v50, s[40:41] offset:1024
	global_store_dword v147, v114, s[40:41] offset:1280
	global_store_dword v147, v51, s[40:41] offset:1536
	global_store_dword v147, v115, s[40:41] offset:1792
	global_store_dword v147, v52, s[40:41] offset:2048
	global_store_dword v147, v116, s[40:41] offset:2304
	global_store_dword v147, v53, s[40:41] offset:2560
	global_store_dword v147, v117, s[40:41] offset:2816
	global_store_dword v147, v54, s[40:41] offset:3072
	global_store_dword v147, v118, s[40:41] offset:3328
	global_store_dword v147, v55, s[40:41] offset:3584
	global_store_dword v147, v119, s[40:41] offset:3840
	v_add_u32_e32 v147, 0x1000, v147
	global_store_dword v147, v56, s[40:41] offset:0
	global_store_dword v147, v120, s[40:41] offset:256
	global_store_dword v147, v57, s[40:41] offset:512
	global_store_dword v147, v121, s[40:41] offset:768
	global_store_dword v147, v58, s[40:41] offset:1024
	global_store_dword v147, v122, s[40:41] offset:1280
	global_store_dword v147, v59, s[40:41] offset:1536
	global_store_dword v147, v123, s[40:41] offset:1792
	global_store_dword v147, v60, s[40:41] offset:2048
	global_store_dword v147, v124, s[40:41] offset:2304
	global_store_dword v147, v61, s[40:41] offset:2560
	global_store_dword v147, v125, s[40:41] offset:2816
	global_store_dword v147, v62, s[40:41] offset:3072
	global_store_dword v147, v126, s[40:41] offset:3328
	global_store_dword v147, v63, s[40:41] offset:3584
	global_store_dword v147, v127, s[40:41] offset:3840
.Lhs_restore:
	v_mov_b64_e32 v[130:131], 0x43f
	v_mov_b64_e32 v[132:133], 0x440
	v_mov_b64_e32 v[134:135], 0xff
	v_mov_b64_e32 v[136:137], 0x100
	v_mov_b64_e32 v[140:141], 0x21f
	v_mov_b64_e32 v[142:143], 0x220
	v_mov_b64_e32 v[144:145], 0x1ff
	v_mov_b64_e32 v[146:147], 0x200
	v_mov_b32_e32 v138, 1.0
	s_branch .LBB0_486
